# BM selected-attention: K fragments of block i+2 issued after the last group's softmax check of block i (prefetch distance about two blocks)
# baseline (speedup 1.0000x reference)
.LBB0_1549:
.LBB0_1550:
	v_readfirstlane_b32 s46, v70
	v_readfirstlane_b32 s47, v71
	v_readfirstlane_b32 s62, v72
	v_readfirstlane_b32 s63, v73
	v_and_b32_e32 v248, 15, v181
	v_lshrrev_b32_e32 v249, 4, v181
	v_lshrrev_b32_e32 v248, 2, v248
	v_lshlrev_b32_e32 v249, 2, v249
	v_readlane_b32 s23, v243, 32
	v_mov_b32_e32 v244, 1
	v_lshlrev_b32_e32 v244, v248, v244
	s_mov_b32 s16, 0x3e38aa3b
	s_mov_b32 s17, 0x3e38aa3b
	v_lshlrev_b32_e32 v79, 4, v181
	s_add_i32 s23, s23, s97
	v_add_u32_e32 v247, s23, v248
	v_mad_u64_u32 v[250:251], s[50:51], v247, v212, v[68:69]
	global_load_dwordx4 v[100:103], v[250:251], off
	global_load_dwordx4 v[104:107], v[250:251], off offset:64
	v_add_u32_e32 v249, 4, v247
	v_mad_u64_u32 v[250:251], s[50:51], v249, v212, v[68:69]
	global_load_dwordx4 v[108:111], v[250:251], off
	global_load_dwordx4 v[112:115], v[250:251], off offset:64
	v_add_u32_e32 v249, 8, v247
	v_mad_u64_u32 v[250:251], s[50:51], v249, v212, v[68:69]
	global_load_dwordx4 v[116:119], v[250:251], off
	global_load_dwordx4 v[120:123], v[250:251], off offset:64
	v_add_u32_e32 v249, 12, v247
	v_mad_u64_u32 v[250:251], s[50:51], v249, v212, v[68:69]
	global_load_dwordx4 v[124:127], v[250:251], off
	global_load_dwordx4 v[128:131], v[250:251], off offset:64
	v_and_b32_e32 v248, 15, v181
	v_lshrrev_b32_e32 v249, 4, v181
	v_lshlrev_b32_e32 v198, 6, v248
	v_lshl_add_u32 v198, v249, 2, v198
	v_add_u32_e32 v198, s96, v198
	v_lshl_add_u32 v199, v248, 2, s96
	ds_read_b32 v12, v198 offset:16384
	ds_read_b32 v13, v198 offset:16400
	ds_read_b32 v14, v198 offset:16416
	ds_read_b32 v15, v198 offset:16432
	ds_read_b32 v16, v199 offset:17408
	v_lshl_add_u32 v199, v181, 2, s96
	v_mov_b32_e32 v17, 1
	v_lshlrev_b32_e32 v17, v248, v17
	s_waitcnt lgkmcnt(0)
	v_mul_f32_e32 v81, 0x3fb8aa3b, v81
	ds_write_b32 v199, v11 offset:16384
	ds_write_b32 v199, v11 offset:16640
	ds_write_b32 v199, v11 offset:16896
	ds_write_b32 v199, v11 offset:17152
	v_cmp_lt_i32_e32 vcc, v249, v16
	v_and_b32_e32 v12, 0xff, v12
	v_lshl_add_u32 v12, v12, 2, s96
	v_cndmask_b32_e32 v18, 0, v17, vcc
	ds_or_b32 v12, v18 offset:16384
	v_add_u32_e32 v18, 4, v249
	v_cmp_lt_i32_e32 vcc, v18, v16
	v_and_b32_e32 v13, 0xff, v13
	v_lshl_add_u32 v13, v13, 2, s96
	v_cndmask_b32_e32 v18, 0, v17, vcc
	ds_or_b32 v13, v18 offset:16384
	v_add_u32_e32 v18, 8, v249
	v_cmp_lt_i32_e32 vcc, v18, v16
	v_and_b32_e32 v14, 0xff, v14
	v_lshl_add_u32 v14, v14, 2, s96
	v_cndmask_b32_e32 v18, 0, v17, vcc
	ds_or_b32 v14, v18 offset:16384
	v_add_u32_e32 v18, 12, v249
	v_cmp_lt_i32_e32 vcc, v18, v16
	v_and_b32_e32 v15, 0xff, v15
	v_lshl_add_u32 v15, v15, 2, s96
	v_cndmask_b32_e32 v18, 0, v17, vcc
	ds_or_b32 v15, v18 offset:16384
	s_waitcnt lgkmcnt(0)
	ds_read_b32 v12, v199 offset:16384
	ds_read_b32 v13, v199 offset:16640
	ds_read_b32 v14, v199 offset:16896
	ds_read_b32 v15, v199 offset:17152
	s_mov_b32 s25, 0
	s_waitcnt lgkmcnt(0)
	v_cmp_ne_u32_e64 s[4:5], 0, v12
	v_lshlrev_b32_e32 v16, 16, v12
	v_add_u32_e32 v17, 0, v181
	v_or_b32_e32 v16, v16, v17
	v_mbcnt_lo_u32_b32 v17, s4, 0
	v_mbcnt_hi_u32_b32 v17, s5, v17
	v_add_u32_e32 v17, s25, v17
	v_lshl_add_u32 v17, v17, 2, s96
	v_add_u32_e32 v17, 0x4000, v17
	v_add_u32_e32 v18, 0x4400, v199
	s_bcnt1_i32_b64 s13, s[4:5]
	v_cndmask_b32_e64 v17, v18, v17, s[4:5]
	s_add_i32 s25, s25, s13
	ds_write_b32 v17, v16
	v_cmp_ne_u32_e64 s[4:5], 0, v13
	v_lshlrev_b32_e32 v16, 16, v13
	v_add_u32_e32 v17, 64, v181
	v_or_b32_e32 v16, v16, v17
	v_mbcnt_lo_u32_b32 v17, s4, 0
	v_mbcnt_hi_u32_b32 v17, s5, v17
	v_add_u32_e32 v17, s25, v17
	v_lshl_add_u32 v17, v17, 2, s96
	v_add_u32_e32 v17, 0x4000, v17
	v_add_u32_e32 v18, 0x4400, v199
	s_bcnt1_i32_b64 s13, s[4:5]
	v_cndmask_b32_e64 v17, v18, v17, s[4:5]
	s_add_i32 s25, s25, s13
	ds_write_b32 v17, v16
	v_cmp_ne_u32_e64 s[4:5], 0, v14
	v_lshlrev_b32_e32 v16, 16, v14
	v_add_u32_e32 v17, 128, v181
	v_or_b32_e32 v16, v16, v17
	v_mbcnt_lo_u32_b32 v17, s4, 0
	v_mbcnt_hi_u32_b32 v17, s5, v17
	v_add_u32_e32 v17, s25, v17
	v_lshl_add_u32 v17, v17, 2, s96
	v_add_u32_e32 v17, 0x4000, v17
	v_add_u32_e32 v18, 0x4400, v199
	s_bcnt1_i32_b64 s13, s[4:5]
	v_cndmask_b32_e64 v17, v18, v17, s[4:5]
	s_add_i32 s25, s25, s13
	ds_write_b32 v17, v16
	v_cmp_ne_u32_e64 s[4:5], 0, v15
	v_lshlrev_b32_e32 v16, 16, v15
	v_add_u32_e32 v17, 192, v181
	v_or_b32_e32 v16, v16, v17
	v_mbcnt_lo_u32_b32 v17, s4, 0
	v_mbcnt_hi_u32_b32 v17, s5, v17
	v_add_u32_e32 v17, s25, v17
	v_lshl_add_u32 v17, v17, 2, s96
	v_add_u32_e32 v17, 0x4000, v17
	v_add_u32_e32 v18, 0x4400, v199
	s_bcnt1_i32_b64 s13, s[4:5]
	v_cndmask_b32_e64 v17, v18, v17, s[4:5]
	s_add_i32 s25, s25, s13
	ds_write_b32 v17, v16
	s_waitcnt vmcnt(0)
	v_lshlrev_b32_e32 v245, 16, v100
	v_and_b32_e32 v246, 0xffff0000, v100
	v_mul_f32_e32 v245, 0x41000000, v245
	v_mul_f32_e32 v246, 0x41000000, v246
	v_lshlrev_b32_e32 v248, 16, v101
	v_and_b32_e32 v249, 0xffff0000, v101
	v_cvt_pk_fp8_f32 v164, v245, v246
	v_mul_f32_e32 v248, 0x41000000, v248
	v_mul_f32_e32 v249, 0x41000000, v249
	s_nop 0
	v_cvt_pk_fp8_f32 v164, v248, v249 op_sel:[0,0,1]
	v_lshlrev_b32_e32 v245, 16, v102
	v_and_b32_e32 v246, 0xffff0000, v102
	v_mul_f32_e32 v245, 0x41000000, v245
	v_mul_f32_e32 v246, 0x41000000, v246
	v_lshlrev_b32_e32 v248, 16, v103
	v_and_b32_e32 v249, 0xffff0000, v103
	v_cvt_pk_fp8_f32 v165, v245, v246
	v_mul_f32_e32 v248, 0x41000000, v248
	v_mul_f32_e32 v249, 0x41000000, v249
	s_nop 0
	v_cvt_pk_fp8_f32 v165, v248, v249 op_sel:[0,0,1]
	v_lshlrev_b32_e32 v245, 16, v104
	v_and_b32_e32 v246, 0xffff0000, v104
	v_mul_f32_e32 v245, 0x41000000, v245
	v_mul_f32_e32 v246, 0x41000000, v246
	v_lshlrev_b32_e32 v248, 16, v105
	v_and_b32_e32 v249, 0xffff0000, v105
	v_cvt_pk_fp8_f32 v166, v245, v246
	v_mul_f32_e32 v248, 0x41000000, v248
	v_mul_f32_e32 v249, 0x41000000, v249
	s_nop 0
	v_cvt_pk_fp8_f32 v166, v248, v249 op_sel:[0,0,1]
	v_lshlrev_b32_e32 v245, 16, v106
	v_and_b32_e32 v246, 0xffff0000, v106
	v_mul_f32_e32 v245, 0x41000000, v245
	v_mul_f32_e32 v246, 0x41000000, v246
	v_lshlrev_b32_e32 v248, 16, v107
	v_and_b32_e32 v249, 0xffff0000, v107
	v_cvt_pk_fp8_f32 v167, v245, v246
	v_mul_f32_e32 v248, 0x41000000, v248
	v_mul_f32_e32 v249, 0x41000000, v249
	s_nop 0
	v_cvt_pk_fp8_f32 v167, v248, v249 op_sel:[0,0,1]
	v_lshlrev_b32_e32 v245, 16, v108
	v_and_b32_e32 v246, 0xffff0000, v108
	v_mul_f32_e32 v245, 0x41000000, v245
	v_mul_f32_e32 v246, 0x41000000, v246
	v_lshlrev_b32_e32 v248, 16, v109
	v_and_b32_e32 v249, 0xffff0000, v109
	v_cvt_pk_fp8_f32 v168, v245, v246
	v_mul_f32_e32 v248, 0x41000000, v248
	v_mul_f32_e32 v249, 0x41000000, v249
	s_nop 0
	v_cvt_pk_fp8_f32 v168, v248, v249 op_sel:[0,0,1]
	v_lshlrev_b32_e32 v245, 16, v110
	v_and_b32_e32 v246, 0xffff0000, v110
	v_mul_f32_e32 v245, 0x41000000, v245
	v_mul_f32_e32 v246, 0x41000000, v246
	v_lshlrev_b32_e32 v248, 16, v111
	v_and_b32_e32 v249, 0xffff0000, v111
	v_cvt_pk_fp8_f32 v169, v245, v246
	v_mul_f32_e32 v248, 0x41000000, v248
	v_mul_f32_e32 v249, 0x41000000, v249
	s_nop 0
	v_cvt_pk_fp8_f32 v169, v248, v249 op_sel:[0,0,1]
	v_lshlrev_b32_e32 v245, 16, v112
	v_and_b32_e32 v246, 0xffff0000, v112
	v_mul_f32_e32 v245, 0x41000000, v245
	v_mul_f32_e32 v246, 0x41000000, v246
	v_lshlrev_b32_e32 v248, 16, v113
	v_and_b32_e32 v249, 0xffff0000, v113
	v_cvt_pk_fp8_f32 v170, v245, v246
	v_mul_f32_e32 v248, 0x41000000, v248
	v_mul_f32_e32 v249, 0x41000000, v249
	s_nop 0
	v_cvt_pk_fp8_f32 v170, v248, v249 op_sel:[0,0,1]
	v_lshlrev_b32_e32 v245, 16, v114
	v_and_b32_e32 v246, 0xffff0000, v114
	v_mul_f32_e32 v245, 0x41000000, v245
	v_mul_f32_e32 v246, 0x41000000, v246
	v_lshlrev_b32_e32 v248, 16, v115
	v_and_b32_e32 v249, 0xffff0000, v115
	v_cvt_pk_fp8_f32 v171, v245, v246
	v_mul_f32_e32 v248, 0x41000000, v248
	v_mul_f32_e32 v249, 0x41000000, v249
	s_nop 0
	v_cvt_pk_fp8_f32 v171, v248, v249 op_sel:[0,0,1]
	v_lshlrev_b32_e32 v245, 16, v116
	v_and_b32_e32 v246, 0xffff0000, v116
	v_mul_f32_e32 v245, 0x41000000, v245
	v_mul_f32_e32 v246, 0x41000000, v246
	v_lshlrev_b32_e32 v248, 16, v117
	v_and_b32_e32 v249, 0xffff0000, v117
	v_cvt_pk_fp8_f32 v182, v245, v246
	v_mul_f32_e32 v248, 0x41000000, v248
	v_mul_f32_e32 v249, 0x41000000, v249
	s_nop 0
	v_cvt_pk_fp8_f32 v182, v248, v249 op_sel:[0,0,1]
	v_lshlrev_b32_e32 v245, 16, v118
	v_and_b32_e32 v246, 0xffff0000, v118
	v_mul_f32_e32 v245, 0x41000000, v245
	v_mul_f32_e32 v246, 0x41000000, v246
	v_lshlrev_b32_e32 v248, 16, v119
	v_and_b32_e32 v249, 0xffff0000, v119
	v_cvt_pk_fp8_f32 v183, v245, v246
	v_mul_f32_e32 v248, 0x41000000, v248
	v_mul_f32_e32 v249, 0x41000000, v249
	s_nop 0
	v_cvt_pk_fp8_f32 v183, v248, v249 op_sel:[0,0,1]
	v_lshlrev_b32_e32 v245, 16, v120
	v_and_b32_e32 v246, 0xffff0000, v120
	v_mul_f32_e32 v245, 0x41000000, v245
	v_mul_f32_e32 v246, 0x41000000, v246
	v_lshlrev_b32_e32 v248, 16, v121
	v_and_b32_e32 v249, 0xffff0000, v121
	v_cvt_pk_fp8_f32 v184, v245, v246
	v_mul_f32_e32 v248, 0x41000000, v248
	v_mul_f32_e32 v249, 0x41000000, v249
	s_nop 0
	v_cvt_pk_fp8_f32 v184, v248, v249 op_sel:[0,0,1]
	v_lshlrev_b32_e32 v245, 16, v122
	v_and_b32_e32 v246, 0xffff0000, v122
	v_mul_f32_e32 v245, 0x41000000, v245
	v_mul_f32_e32 v246, 0x41000000, v246
	v_lshlrev_b32_e32 v248, 16, v123
	v_and_b32_e32 v249, 0xffff0000, v123
	v_cvt_pk_fp8_f32 v185, v245, v246
	v_mul_f32_e32 v248, 0x41000000, v248
	v_mul_f32_e32 v249, 0x41000000, v249
	s_nop 0
	v_cvt_pk_fp8_f32 v185, v248, v249 op_sel:[0,0,1]
	v_lshlrev_b32_e32 v245, 16, v124
	v_and_b32_e32 v246, 0xffff0000, v124
	v_mul_f32_e32 v245, 0x41000000, v245
	v_mul_f32_e32 v246, 0x41000000, v246
	v_lshlrev_b32_e32 v248, 16, v125
	v_and_b32_e32 v249, 0xffff0000, v125
	v_cvt_pk_fp8_f32 v186, v245, v246
	v_mul_f32_e32 v248, 0x41000000, v248
	v_mul_f32_e32 v249, 0x41000000, v249
	s_nop 0
	v_cvt_pk_fp8_f32 v186, v248, v249 op_sel:[0,0,1]
	v_lshlrev_b32_e32 v245, 16, v126
	v_and_b32_e32 v246, 0xffff0000, v126
	v_mul_f32_e32 v245, 0x41000000, v245
	v_mul_f32_e32 v246, 0x41000000, v246
	v_lshlrev_b32_e32 v248, 16, v127
	v_and_b32_e32 v249, 0xffff0000, v127
	v_cvt_pk_fp8_f32 v187, v245, v246
	v_mul_f32_e32 v248, 0x41000000, v248
	v_mul_f32_e32 v249, 0x41000000, v249
	s_nop 0
	v_cvt_pk_fp8_f32 v187, v248, v249 op_sel:[0,0,1]
	v_lshlrev_b32_e32 v245, 16, v128
	v_and_b32_e32 v246, 0xffff0000, v128
	v_mul_f32_e32 v245, 0x41000000, v245
	v_mul_f32_e32 v246, 0x41000000, v246
	v_lshlrev_b32_e32 v248, 16, v129
	v_and_b32_e32 v249, 0xffff0000, v129
	v_cvt_pk_fp8_f32 v188, v245, v246
	v_mul_f32_e32 v248, 0x41000000, v248
	v_mul_f32_e32 v249, 0x41000000, v249
	s_nop 0
	v_cvt_pk_fp8_f32 v188, v248, v249 op_sel:[0,0,1]
	v_lshlrev_b32_e32 v245, 16, v130
	v_and_b32_e32 v246, 0xffff0000, v130
	v_mul_f32_e32 v245, 0x41000000, v245
	v_mul_f32_e32 v246, 0x41000000, v246
	v_lshlrev_b32_e32 v248, 16, v131
	v_and_b32_e32 v249, 0xffff0000, v131
	v_cvt_pk_fp8_f32 v189, v245, v246
	v_mul_f32_e32 v248, 0x41000000, v248
	v_mul_f32_e32 v249, 0x41000000, v249
	s_nop 0
	v_cvt_pk_fp8_f32 v189, v248, v249 op_sel:[0,0,1]
	v_mov_b64_e32 v[100:101], 0
	v_mov_b64_e32 v[102:103], 0
	v_mov_b64_e32 v[104:105], 0
	v_mov_b64_e32 v[106:107], 0
	v_mov_b64_e32 v[108:109], 0
	v_mov_b64_e32 v[110:111], 0
	v_mov_b64_e32 v[112:113], 0
	v_mov_b64_e32 v[114:115], 0
	v_mov_b32_e32 v190, 0
	v_mov_b32_e32 v194, 0
	v_mov_b64_e32 v[116:117], 0
	v_mov_b64_e32 v[118:119], 0
	v_mov_b64_e32 v[120:121], 0
	v_mov_b64_e32 v[122:123], 0
	v_mov_b64_e32 v[124:125], 0
	v_mov_b64_e32 v[126:127], 0
	v_mov_b64_e32 v[128:129], 0
	v_mov_b64_e32 v[130:131], 0
	v_mov_b32_e32 v191, 0
	v_mov_b32_e32 v195, 0
	v_mov_b64_e32 v[132:133], 0
	v_mov_b64_e32 v[134:135], 0
	v_mov_b64_e32 v[136:137], 0
	v_mov_b64_e32 v[138:139], 0
	v_mov_b64_e32 v[140:141], 0
	v_mov_b64_e32 v[142:143], 0
	v_mov_b64_e32 v[144:145], 0
	v_mov_b64_e32 v[146:147], 0
	v_mov_b32_e32 v192, 0
	v_mov_b32_e32 v196, 0
	v_mov_b64_e32 v[148:149], 0
	v_mov_b64_e32 v[150:151], 0
	v_mov_b64_e32 v[152:153], 0
	v_mov_b64_e32 v[154:155], 0
	v_mov_b64_e32 v[156:157], 0
	v_mov_b64_e32 v[158:159], 0
	v_mov_b64_e32 v[160:161], 0
	v_mov_b64_e32 v[162:163], 0
	v_mov_b32_e32 v193, 0
	v_mov_b32_e32 v197, 0
	v_mov_b32_e32 v77, 0xff800000
	v_mov_b32_e32 v78, 0xff800000
	s_waitcnt lgkmcnt(0)
	s_mov_b32 s35, 0
	s_lshl_b32 s13, s35, 2
	s_add_i32 s13, s13, s96
	v_mov_b32_e32 v76, s13
	ds_read_b32 v76, v76 offset:16384
	s_add_i32 s14, s25, -1
	s_min_i32 s14, s14, 1
	s_waitcnt lgkmcnt(0)
	v_readfirstlane_b32 s13, v76
	s_and_b32 s54, s13, 0xffff
	s_lshr_b32 s48, s13, 16
	s_lshl_b32 s13, s14, 2
	s_add_i32 s13, s13, s96
	v_mov_b32_e32 v76, s13
	ds_read_b32 v76, v76 offset:16384
	s_lshl_b32 s12, s54, 12
	s_add_u32 s30, s46, s12
	s_addc_u32 s31, s47, 0
	global_load_dwordx4 v[2:5], v79, s[30:31]
	global_load_dwordx4 v[6:9], v79, s[30:31] offset:1024
	global_load_dwordx4 v[12:15], v79, s[30:31] offset:2048
	global_load_dwordx4 v[16:19], v79, s[30:31] offset:3072
	s_lshl_b32 s12, s54, 12
	s_add_u32 s30, s62, s12
	s_addc_u32 s31, s63, 0
	global_load_dwordx4 v[36:39], v79, s[30:31]
	global_load_dwordx4 v[40:43], v79, s[30:31] offset:1024
	global_load_dwordx4 v[44:47], v79, s[30:31] offset:2048
	global_load_dwordx4 v[48:51], v79, s[30:31] offset:3072
	s_waitcnt lgkmcnt(0)
	v_readfirstlane_b32 s13, v76
	s_and_b32 s15, s13, 0xffff
	s_lshr_b32 s27, s13, 16
	s_add_i32 s83, s25, -1
	s_min_i32 s83, s83, 2
	s_lshl_b32 s83, s83, 2
	s_add_i32 s83, s83, s96
	v_mov_b32_e32 v76, s83
	ds_read_b32 v76, v76 offset:16384
	s_lshl_b32 s83, s15, 12
	s_add_u32 s30, s46, s83
	s_addc_u32 s31, s47, 0
	global_load_dwordx4 v[20:23], v79, s[30:31]
	global_load_dwordx4 v[24:27], v79, s[30:31] offset:1024
	global_load_dwordx4 v[28:31], v79, s[30:31] offset:2048
	global_load_dwordx4 v[32:35], v79, s[30:31] offset:3072
	s_waitcnt lgkmcnt(0)
	v_readfirstlane_b32 s13, v76
	s_and_b32 s32, s13, 0xffff
	s_lshr_b32 s55, s13, 16
	v_readfirstlane_b32 s83, v1
	s_bitcmp1_b32 s83, 8
	s_cbranch_scc0 .Lbm2_nostag
	s_sleep 4
.Lbm2_nostag:
.Lbm2_blkA:
	s_lshl_b32 s12, s15, 12
	s_add_u32 s30, s62, s12
	s_addc_u32 s31, s63, 0
	global_load_dwordx4 v[52:55], v79, s[30:31]
	global_load_dwordx4 v[56:59], v79, s[30:31] offset:1024
	global_load_dwordx4 v[60:63], v79, s[30:31] offset:2048
	global_load_dwordx4 v[64:67], v79, s[30:31] offset:3072
	s_add_i32 s14, s35, 3
	s_add_i32 s13, s25, -1
	s_min_i32 s14, s14, s13
	s_lshl_b32 s13, s14, 2
	s_add_i32 s13, s13, s96
	v_mov_b32_e32 v76, s13
	ds_read_b32 v76, v76 offset:16384
	s_cmp_ge_i32 s54, s21
	s_cselect_b32 s14, 1, 0
	s_bfe_u32 s29, s48, 0x40000
	s_cmp_eq_u32 s29, 0
	s_cbranch_scc1 .Lbm2_Ag0_skip
	s_waitcnt vmcnt(12)
	v_mfma_f32_16x16x32_fp8_fp8 v[84:87], v[2:3], v[164:165], 0
	v_mfma_f32_16x16x32_fp8_fp8 v[84:87], v[4:5], v[166:167], v[84:87]
	v_mfma_f32_16x16x32_fp8_fp8 v[88:91], v[6:7], v[164:165], 0
	v_mfma_f32_16x16x32_fp8_fp8 v[88:91], v[8:9], v[166:167], v[88:91]
	v_and_b32_e32 v199, s29, v244
	s_cmp_eq_u32 s14, 1
	v_cmp_ne_u32_e32 vcc, 0, v199
	s_cbranch_scc1 .Lbm2_Ag0_near0
	v_add_f32_e32 v200, v81, v190
	v_cndmask_b32_e32 v200, v77, v200, vcc
	s_cmp_eq_u32 s35, 0
	s_cbranch_scc1 .Lbm2_Ag0_first0
	v_mfma_f32_16x16x32_fp8_fp8 v[92:95], v[12:13], v[164:165], 0
	v_mfma_f32_16x16x32_fp8_fp8 v[92:95], v[14:15], v[166:167], v[92:95]
	v_pk_fma_f32 v[84:85], v[84:85], s[16:17], v[200:201] op_sel_hi:[1,1,0]
	v_pk_fma_f32 v[86:87], v[86:87], s[16:17], v[200:201] op_sel_hi:[1,1,0]
	v_mfma_f32_16x16x32_fp8_fp8 v[96:99], v[16:17], v[164:165], 0
	v_mfma_f32_16x16x32_fp8_fp8 v[96:99], v[18:19], v[166:167], v[96:99]
	v_exp_f32_e32 v84, v84
	v_exp_f32_e32 v85, v85
	v_exp_f32_e32 v86, v86
	v_exp_f32_e32 v87, v87
	v_pk_fma_f32 v[88:89], v[88:89], s[16:17], v[200:201] op_sel_hi:[1,1,0]
	v_pk_fma_f32 v[90:91], v[90:91], s[16:17], v[200:201] op_sel_hi:[1,1,0]
	v_exp_f32_e32 v88, v88
	v_exp_f32_e32 v89, v89
	v_exp_f32_e32 v90, v90
	v_exp_f32_e32 v91, v91
	v_pk_fma_f32 v[92:93], v[92:93], s[16:17], v[200:201] op_sel_hi:[1,1,0]
	v_pk_fma_f32 v[94:95], v[94:95], s[16:17], v[200:201] op_sel_hi:[1,1,0]
	v_pk_fma_f32 v[96:97], v[96:97], s[16:17], v[200:201] op_sel_hi:[1,1,0]
	v_pk_fma_f32 v[98:99], v[98:99], s[16:17], v[200:201] op_sel_hi:[1,1,0]
	v_exp_f32_e32 v92, v92
	v_exp_f32_e32 v93, v93
	v_exp_f32_e32 v94, v94
	v_exp_f32_e32 v95, v95
	s_nop 0
	v_exp_f32_e32 v96, v96
	v_exp_f32_e32 v97, v97
	v_exp_f32_e32 v98, v98
	v_exp_f32_e32 v99, v99
	v_pk_add_f32 v[248:249], v[84:85], v[86:87]
	v_pk_add_f32 v[82:83], v[88:89], v[90:91]
	v_pk_add_f32 v[172:173], v[92:93], v[94:95]
	v_pk_add_f32 v[202:203], v[96:97], v[98:99]
	v_cvt_pk_fp8_f32 v84, v84, v85
	v_cvt_pk_fp8_f32 v85, v88, v89
	v_pk_add_f32 v[248:249], v[248:249], v[82:83]
	v_pk_add_f32 v[172:173], v[172:173], v[202:203]
	v_cvt_pk_fp8_f32 v84, v86, v87 op_sel:[0,0,1]
	v_cvt_pk_fp8_f32 v85, v90, v91 op_sel:[0,0,1]
	v_pk_add_f32 v[248:249], v[248:249], v[172:173]
	v_cvt_pk_fp8_f32 v86, v92, v93
	v_cvt_pk_fp8_f32 v87, v96, v97
	v_add_f32_e32 v248, v248, v249
	v_cvt_pk_fp8_f32 v86, v94, v95 op_sel:[0,0,1]
	v_cvt_pk_fp8_f32 v87, v98, v99 op_sel:[0,0,1]
	v_cmp_lt_f32_e32 vcc, 0x43800000, v248
	s_cbranch_vccnz .Lbm2_Ag0_redo
	s_lshr_b32 s83, s48, 4
	s_cmp_lg_u32 s83, 0
	s_cbranch_scc1 .Lbm2_Ag0_ks0
	s_lshl_b32 s83, s32, 12
	s_add_u32 s30, s46, s83
	s_addc_u32 s31, s47, 0
	global_load_dwordx4 v[2:5], v79, s[30:31]
	global_load_dwordx4 v[6:9], v79, s[30:31] offset:1024
	global_load_dwordx4 v[12:15], v79, s[30:31] offset:2048
	global_load_dwordx4 v[16:19], v79, s[30:31] offset:3072
.Lbm2_Ag0_ks0:
	v_add_f32_e32 v194, v194, v248
	s_waitcnt vmcnt(8)
	v_mfma_f32_16x16x32_fp8_fp8 v[100:103], v[36:37], v[84:85], v[100:103]
	v_mfma_f32_16x16x32_fp8_fp8 v[104:107], v[38:39], v[84:85], v[104:107]
	v_mfma_f32_16x16x32_fp8_fp8 v[108:111], v[40:41], v[84:85], v[108:111]
	v_mfma_f32_16x16x32_fp8_fp8 v[112:115], v[42:43], v[84:85], v[112:115]
	v_mfma_f32_16x16x32_fp8_fp8 v[100:103], v[44:45], v[86:87], v[100:103]
	v_mfma_f32_16x16x32_fp8_fp8 v[104:107], v[46:47], v[86:87], v[104:107]
	v_mfma_f32_16x16x32_fp8_fp8 v[108:111], v[48:49], v[86:87], v[108:111]
	v_mfma_f32_16x16x32_fp8_fp8 v[112:115], v[50:51], v[86:87], v[112:115]
	s_branch .Lbm2_Ag0_skip

.Lbm2_Ag0_exp:
	v_exp_f32_e32 v84, v84
	v_exp_f32_e32 v85, v85
	v_exp_f32_e32 v86, v86
	v_exp_f32_e32 v87, v87
	v_exp_f32_e32 v88, v88
	v_exp_f32_e32 v89, v89
	v_exp_f32_e32 v90, v90
	v_exp_f32_e32 v91, v91
	v_exp_f32_e32 v92, v92
	v_exp_f32_e32 v93, v93
	v_exp_f32_e32 v94, v94
	v_exp_f32_e32 v95, v95
	v_exp_f32_e32 v96, v96
	v_exp_f32_e32 v97, v97
	v_exp_f32_e32 v98, v98
	v_exp_f32_e32 v99, v99
	v_pk_add_f32 v[248:249], v[84:85], v[86:87]
	v_pk_add_f32 v[248:249], v[248:249], v[88:89]
	v_pk_add_f32 v[248:249], v[248:249], v[90:91]
	v_pk_add_f32 v[248:249], v[248:249], v[92:93]
	v_pk_add_f32 v[248:249], v[248:249], v[94:95]
	v_pk_add_f32 v[248:249], v[248:249], v[96:97]
	v_pk_add_f32 v[248:249], v[248:249], v[98:99]
	v_cvt_pk_fp8_f32 v84, v84, v85
	v_cvt_pk_fp8_f32 v85, v88, v89
	v_cvt_pk_fp8_f32 v84, v86, v87 op_sel:[0,0,1]
	v_cvt_pk_fp8_f32 v85, v90, v91 op_sel:[0,0,1]
	v_cvt_pk_fp8_f32 v86, v92, v93
	v_cvt_pk_fp8_f32 v87, v96, v97
	v_cvt_pk_fp8_f32 v86, v94, v95 op_sel:[0,0,1]
	v_cvt_pk_fp8_f32 v87, v98, v99 op_sel:[0,0,1]
	v_add_f32_e32 v248, v248, v249
	v_add_f32_e32 v194, v194, v248
	s_lshr_b32 s83, s48, 4
	s_cmp_lg_u32 s83, 0
	s_cbranch_scc1 .Lbm2_Ag0_ks1
	s_lshl_b32 s83, s32, 12
	s_add_u32 s30, s46, s83
	s_addc_u32 s31, s47, 0
	global_load_dwordx4 v[2:5], v79, s[30:31]
	global_load_dwordx4 v[6:9], v79, s[30:31] offset:1024
	global_load_dwordx4 v[12:15], v79, s[30:31] offset:2048
	global_load_dwordx4 v[16:19], v79, s[30:31] offset:3072
.Lbm2_Ag0_ks1:
	s_waitcnt vmcnt(8)
	v_mfma_f32_16x16x32_fp8_fp8 v[100:103], v[36:37], v[84:85], v[100:103]
	v_mfma_f32_16x16x32_fp8_fp8 v[104:107], v[38:39], v[84:85], v[104:107]
	v_mfma_f32_16x16x32_fp8_fp8 v[108:111], v[40:41], v[84:85], v[108:111]
	v_mfma_f32_16x16x32_fp8_fp8 v[112:115], v[42:43], v[84:85], v[112:115]
	v_mfma_f32_16x16x32_fp8_fp8 v[100:103], v[44:45], v[86:87], v[100:103]
	v_mfma_f32_16x16x32_fp8_fp8 v[104:107], v[46:47], v[86:87], v[104:107]
	v_mfma_f32_16x16x32_fp8_fp8 v[108:111], v[48:49], v[86:87], v[108:111]
	v_mfma_f32_16x16x32_fp8_fp8 v[112:115], v[50:51], v[86:87], v[112:115]
	s_branch .Lbm2_Ag0_skip

.Lbm2_Ag0_skip:
	s_bfe_u32 s29, s48, 0x40004
	s_cmp_eq_u32 s29, 0
	s_cbranch_scc1 .Lbm2_Ag1_skip
	s_waitcnt vmcnt(12)
	v_mfma_f32_16x16x32_fp8_fp8 v[84:87], v[2:3], v[168:169], 0
	v_mfma_f32_16x16x32_fp8_fp8 v[84:87], v[4:5], v[170:171], v[84:87]
	v_mfma_f32_16x16x32_fp8_fp8 v[88:91], v[6:7], v[168:169], 0
	v_mfma_f32_16x16x32_fp8_fp8 v[88:91], v[8:9], v[170:171], v[88:91]
	v_and_b32_e32 v199, s29, v244
	s_cmp_eq_u32 s14, 1
	v_cmp_ne_u32_e32 vcc, 0, v199
	s_cbranch_scc1 .Lbm2_Ag1_near0
	v_add_f32_e32 v200, v81, v191
	v_cndmask_b32_e32 v200, v77, v200, vcc
	s_cmp_eq_u32 s35, 0
	s_cbranch_scc1 .Lbm2_Ag1_first0
	v_mfma_f32_16x16x32_fp8_fp8 v[92:95], v[12:13], v[168:169], 0
	v_mfma_f32_16x16x32_fp8_fp8 v[92:95], v[14:15], v[170:171], v[92:95]
	v_pk_fma_f32 v[84:85], v[84:85], s[16:17], v[200:201] op_sel_hi:[1,1,0]
	v_pk_fma_f32 v[86:87], v[86:87], s[16:17], v[200:201] op_sel_hi:[1,1,0]
	v_mfma_f32_16x16x32_fp8_fp8 v[96:99], v[16:17], v[168:169], 0
	v_mfma_f32_16x16x32_fp8_fp8 v[96:99], v[18:19], v[170:171], v[96:99]
	v_exp_f32_e32 v84, v84
	v_exp_f32_e32 v85, v85
	v_exp_f32_e32 v86, v86
	v_exp_f32_e32 v87, v87
	v_pk_fma_f32 v[88:89], v[88:89], s[16:17], v[200:201] op_sel_hi:[1,1,0]
	v_pk_fma_f32 v[90:91], v[90:91], s[16:17], v[200:201] op_sel_hi:[1,1,0]
	v_exp_f32_e32 v88, v88
	v_exp_f32_e32 v89, v89
	v_exp_f32_e32 v90, v90
	v_exp_f32_e32 v91, v91
	v_pk_fma_f32 v[92:93], v[92:93], s[16:17], v[200:201] op_sel_hi:[1,1,0]
	v_pk_fma_f32 v[94:95], v[94:95], s[16:17], v[200:201] op_sel_hi:[1,1,0]
	v_pk_fma_f32 v[96:97], v[96:97], s[16:17], v[200:201] op_sel_hi:[1,1,0]
	v_pk_fma_f32 v[98:99], v[98:99], s[16:17], v[200:201] op_sel_hi:[1,1,0]
	v_exp_f32_e32 v92, v92
	v_exp_f32_e32 v93, v93
	v_exp_f32_e32 v94, v94
	v_exp_f32_e32 v95, v95
	s_nop 0
	v_exp_f32_e32 v96, v96
	v_exp_f32_e32 v97, v97
	v_exp_f32_e32 v98, v98
	v_exp_f32_e32 v99, v99
	v_pk_add_f32 v[248:249], v[84:85], v[86:87]
	v_pk_add_f32 v[82:83], v[88:89], v[90:91]
	v_pk_add_f32 v[172:173], v[92:93], v[94:95]
	v_pk_add_f32 v[202:203], v[96:97], v[98:99]
	v_cvt_pk_fp8_f32 v84, v84, v85
	v_cvt_pk_fp8_f32 v85, v88, v89
	v_pk_add_f32 v[248:249], v[248:249], v[82:83]
	v_pk_add_f32 v[172:173], v[172:173], v[202:203]
	v_cvt_pk_fp8_f32 v84, v86, v87 op_sel:[0,0,1]
	v_cvt_pk_fp8_f32 v85, v90, v91 op_sel:[0,0,1]
	v_pk_add_f32 v[248:249], v[248:249], v[172:173]
	v_cvt_pk_fp8_f32 v86, v92, v93
	v_cvt_pk_fp8_f32 v87, v96, v97
	v_add_f32_e32 v248, v248, v249
	v_cvt_pk_fp8_f32 v86, v94, v95 op_sel:[0,0,1]
	v_cvt_pk_fp8_f32 v87, v98, v99 op_sel:[0,0,1]
	v_cmp_lt_f32_e32 vcc, 0x43800000, v248
	s_cbranch_vccnz .Lbm2_Ag1_redo
	s_lshr_b32 s83, s48, 8
	s_cmp_lg_u32 s83, 0
	s_cbranch_scc1 .Lbm2_Ag1_ks0
	s_lshl_b32 s83, s32, 12
	s_add_u32 s30, s46, s83
	s_addc_u32 s31, s47, 0
	global_load_dwordx4 v[2:5], v79, s[30:31]
	global_load_dwordx4 v[6:9], v79, s[30:31] offset:1024
	global_load_dwordx4 v[12:15], v79, s[30:31] offset:2048
	global_load_dwordx4 v[16:19], v79, s[30:31] offset:3072
.Lbm2_Ag1_ks0:
	v_add_f32_e32 v195, v195, v248
	s_waitcnt vmcnt(8)
	v_mfma_f32_16x16x32_fp8_fp8 v[116:119], v[36:37], v[84:85], v[116:119]
	v_mfma_f32_16x16x32_fp8_fp8 v[120:123], v[38:39], v[84:85], v[120:123]
	v_mfma_f32_16x16x32_fp8_fp8 v[124:127], v[40:41], v[84:85], v[124:127]
	v_mfma_f32_16x16x32_fp8_fp8 v[128:131], v[42:43], v[84:85], v[128:131]
	v_mfma_f32_16x16x32_fp8_fp8 v[116:119], v[44:45], v[86:87], v[116:119]
	v_mfma_f32_16x16x32_fp8_fp8 v[120:123], v[46:47], v[86:87], v[120:123]
	v_mfma_f32_16x16x32_fp8_fp8 v[124:127], v[48:49], v[86:87], v[124:127]
	v_mfma_f32_16x16x32_fp8_fp8 v[128:131], v[50:51], v[86:87], v[128:131]
	s_branch .Lbm2_Ag1_skip

.Lbm2_Ag1_exp:
	v_exp_f32_e32 v84, v84
	v_exp_f32_e32 v85, v85
	v_exp_f32_e32 v86, v86
	v_exp_f32_e32 v87, v87
	v_exp_f32_e32 v88, v88
	v_exp_f32_e32 v89, v89
	v_exp_f32_e32 v90, v90
	v_exp_f32_e32 v91, v91
	v_exp_f32_e32 v92, v92
	v_exp_f32_e32 v93, v93
	v_exp_f32_e32 v94, v94
	v_exp_f32_e32 v95, v95
	v_exp_f32_e32 v96, v96
	v_exp_f32_e32 v97, v97
	v_exp_f32_e32 v98, v98
	v_exp_f32_e32 v99, v99
	v_pk_add_f32 v[248:249], v[84:85], v[86:87]
	v_pk_add_f32 v[248:249], v[248:249], v[88:89]
	v_pk_add_f32 v[248:249], v[248:249], v[90:91]
	v_pk_add_f32 v[248:249], v[248:249], v[92:93]
	v_pk_add_f32 v[248:249], v[248:249], v[94:95]
	v_pk_add_f32 v[248:249], v[248:249], v[96:97]
	v_pk_add_f32 v[248:249], v[248:249], v[98:99]
	v_cvt_pk_fp8_f32 v84, v84, v85
	v_cvt_pk_fp8_f32 v85, v88, v89
	v_cvt_pk_fp8_f32 v84, v86, v87 op_sel:[0,0,1]
	v_cvt_pk_fp8_f32 v85, v90, v91 op_sel:[0,0,1]
	v_cvt_pk_fp8_f32 v86, v92, v93
	v_cvt_pk_fp8_f32 v87, v96, v97
	v_cvt_pk_fp8_f32 v86, v94, v95 op_sel:[0,0,1]
	v_cvt_pk_fp8_f32 v87, v98, v99 op_sel:[0,0,1]
	v_add_f32_e32 v248, v248, v249
	v_add_f32_e32 v195, v195, v248
	s_lshr_b32 s83, s48, 8
	s_cmp_lg_u32 s83, 0
	s_cbranch_scc1 .Lbm2_Ag1_ks1
	s_lshl_b32 s83, s32, 12
	s_add_u32 s30, s46, s83
	s_addc_u32 s31, s47, 0
	global_load_dwordx4 v[2:5], v79, s[30:31]
	global_load_dwordx4 v[6:9], v79, s[30:31] offset:1024
	global_load_dwordx4 v[12:15], v79, s[30:31] offset:2048
	global_load_dwordx4 v[16:19], v79, s[30:31] offset:3072
.Lbm2_Ag1_ks1:
	s_waitcnt vmcnt(8)
	v_mfma_f32_16x16x32_fp8_fp8 v[116:119], v[36:37], v[84:85], v[116:119]
	v_mfma_f32_16x16x32_fp8_fp8 v[120:123], v[38:39], v[84:85], v[120:123]
	v_mfma_f32_16x16x32_fp8_fp8 v[124:127], v[40:41], v[84:85], v[124:127]
	v_mfma_f32_16x16x32_fp8_fp8 v[128:131], v[42:43], v[84:85], v[128:131]
	v_mfma_f32_16x16x32_fp8_fp8 v[116:119], v[44:45], v[86:87], v[116:119]
	v_mfma_f32_16x16x32_fp8_fp8 v[120:123], v[46:47], v[86:87], v[120:123]
	v_mfma_f32_16x16x32_fp8_fp8 v[124:127], v[48:49], v[86:87], v[124:127]
	v_mfma_f32_16x16x32_fp8_fp8 v[128:131], v[50:51], v[86:87], v[128:131]
	s_branch .Lbm2_Ag1_skip

.Lbm2_Ag1_skip:
	s_bfe_u32 s29, s48, 0x40008
	s_cmp_eq_u32 s29, 0
	s_cbranch_scc1 .Lbm2_Ag2_skip
	s_waitcnt vmcnt(12)
	v_mfma_f32_16x16x32_fp8_fp8 v[84:87], v[2:3], v[182:183], 0
	v_mfma_f32_16x16x32_fp8_fp8 v[84:87], v[4:5], v[184:185], v[84:87]
	v_mfma_f32_16x16x32_fp8_fp8 v[88:91], v[6:7], v[182:183], 0
	v_mfma_f32_16x16x32_fp8_fp8 v[88:91], v[8:9], v[184:185], v[88:91]
	v_and_b32_e32 v199, s29, v244
	s_cmp_eq_u32 s14, 1
	v_cmp_ne_u32_e32 vcc, 0, v199
	s_cbranch_scc1 .Lbm2_Ag2_near0
	v_add_f32_e32 v200, v81, v192
	v_cndmask_b32_e32 v200, v77, v200, vcc
	s_cmp_eq_u32 s35, 0
	s_cbranch_scc1 .Lbm2_Ag2_first0
	v_mfma_f32_16x16x32_fp8_fp8 v[92:95], v[12:13], v[182:183], 0
	v_mfma_f32_16x16x32_fp8_fp8 v[92:95], v[14:15], v[184:185], v[92:95]
	v_pk_fma_f32 v[84:85], v[84:85], s[16:17], v[200:201] op_sel_hi:[1,1,0]
	v_pk_fma_f32 v[86:87], v[86:87], s[16:17], v[200:201] op_sel_hi:[1,1,0]
	v_mfma_f32_16x16x32_fp8_fp8 v[96:99], v[16:17], v[182:183], 0
	v_mfma_f32_16x16x32_fp8_fp8 v[96:99], v[18:19], v[184:185], v[96:99]
	v_exp_f32_e32 v84, v84
	v_exp_f32_e32 v85, v85
	v_exp_f32_e32 v86, v86
	v_exp_f32_e32 v87, v87
	v_pk_fma_f32 v[88:89], v[88:89], s[16:17], v[200:201] op_sel_hi:[1,1,0]
	v_pk_fma_f32 v[90:91], v[90:91], s[16:17], v[200:201] op_sel_hi:[1,1,0]
	v_exp_f32_e32 v88, v88
	v_exp_f32_e32 v89, v89
	v_exp_f32_e32 v90, v90
	v_exp_f32_e32 v91, v91
	v_pk_fma_f32 v[92:93], v[92:93], s[16:17], v[200:201] op_sel_hi:[1,1,0]
	v_pk_fma_f32 v[94:95], v[94:95], s[16:17], v[200:201] op_sel_hi:[1,1,0]
	v_pk_fma_f32 v[96:97], v[96:97], s[16:17], v[200:201] op_sel_hi:[1,1,0]
	v_pk_fma_f32 v[98:99], v[98:99], s[16:17], v[200:201] op_sel_hi:[1,1,0]
	v_exp_f32_e32 v92, v92
	v_exp_f32_e32 v93, v93
	v_exp_f32_e32 v94, v94
	v_exp_f32_e32 v95, v95
	s_nop 0
	v_exp_f32_e32 v96, v96
	v_exp_f32_e32 v97, v97
	v_exp_f32_e32 v98, v98
	v_exp_f32_e32 v99, v99
	v_pk_add_f32 v[248:249], v[84:85], v[86:87]
	v_pk_add_f32 v[82:83], v[88:89], v[90:91]
	v_pk_add_f32 v[172:173], v[92:93], v[94:95]
	v_pk_add_f32 v[202:203], v[96:97], v[98:99]
	v_cvt_pk_fp8_f32 v84, v84, v85
	v_cvt_pk_fp8_f32 v85, v88, v89
	v_pk_add_f32 v[248:249], v[248:249], v[82:83]
	v_pk_add_f32 v[172:173], v[172:173], v[202:203]
	v_cvt_pk_fp8_f32 v84, v86, v87 op_sel:[0,0,1]
	v_cvt_pk_fp8_f32 v85, v90, v91 op_sel:[0,0,1]
	v_pk_add_f32 v[248:249], v[248:249], v[172:173]
	v_cvt_pk_fp8_f32 v86, v92, v93
	v_cvt_pk_fp8_f32 v87, v96, v97
	v_add_f32_e32 v248, v248, v249
	v_cvt_pk_fp8_f32 v86, v94, v95 op_sel:[0,0,1]
	v_cvt_pk_fp8_f32 v87, v98, v99 op_sel:[0,0,1]
	v_cmp_lt_f32_e32 vcc, 0x43800000, v248
	s_cbranch_vccnz .Lbm2_Ag2_redo
	s_lshr_b32 s83, s48, 12
	s_cmp_lg_u32 s83, 0
	s_cbranch_scc1 .Lbm2_Ag2_ks0
	s_lshl_b32 s83, s32, 12
	s_add_u32 s30, s46, s83
	s_addc_u32 s31, s47, 0
	global_load_dwordx4 v[2:5], v79, s[30:31]
	global_load_dwordx4 v[6:9], v79, s[30:31] offset:1024
	global_load_dwordx4 v[12:15], v79, s[30:31] offset:2048
	global_load_dwordx4 v[16:19], v79, s[30:31] offset:3072
.Lbm2_Ag2_ks0:
	v_add_f32_e32 v196, v196, v248
	s_waitcnt vmcnt(8)
	v_mfma_f32_16x16x32_fp8_fp8 v[132:135], v[36:37], v[84:85], v[132:135]
	v_mfma_f32_16x16x32_fp8_fp8 v[136:139], v[38:39], v[84:85], v[136:139]
	v_mfma_f32_16x16x32_fp8_fp8 v[140:143], v[40:41], v[84:85], v[140:143]
	v_mfma_f32_16x16x32_fp8_fp8 v[144:147], v[42:43], v[84:85], v[144:147]
	v_mfma_f32_16x16x32_fp8_fp8 v[132:135], v[44:45], v[86:87], v[132:135]
	v_mfma_f32_16x16x32_fp8_fp8 v[136:139], v[46:47], v[86:87], v[136:139]
	v_mfma_f32_16x16x32_fp8_fp8 v[140:143], v[48:49], v[86:87], v[140:143]
	v_mfma_f32_16x16x32_fp8_fp8 v[144:147], v[50:51], v[86:87], v[144:147]
	s_branch .Lbm2_Ag2_skip

.Lbm2_Ag2_exp:
	v_exp_f32_e32 v84, v84
	v_exp_f32_e32 v85, v85
	v_exp_f32_e32 v86, v86
	v_exp_f32_e32 v87, v87
	v_exp_f32_e32 v88, v88
	v_exp_f32_e32 v89, v89
	v_exp_f32_e32 v90, v90
	v_exp_f32_e32 v91, v91
	v_exp_f32_e32 v92, v92
	v_exp_f32_e32 v93, v93
	v_exp_f32_e32 v94, v94
	v_exp_f32_e32 v95, v95
	v_exp_f32_e32 v96, v96
	v_exp_f32_e32 v97, v97
	v_exp_f32_e32 v98, v98
	v_exp_f32_e32 v99, v99
	v_pk_add_f32 v[248:249], v[84:85], v[86:87]
	v_pk_add_f32 v[248:249], v[248:249], v[88:89]
	v_pk_add_f32 v[248:249], v[248:249], v[90:91]
	v_pk_add_f32 v[248:249], v[248:249], v[92:93]
	v_pk_add_f32 v[248:249], v[248:249], v[94:95]
	v_pk_add_f32 v[248:249], v[248:249], v[96:97]
	v_pk_add_f32 v[248:249], v[248:249], v[98:99]
	v_cvt_pk_fp8_f32 v84, v84, v85
	v_cvt_pk_fp8_f32 v85, v88, v89
	v_cvt_pk_fp8_f32 v84, v86, v87 op_sel:[0,0,1]
	v_cvt_pk_fp8_f32 v85, v90, v91 op_sel:[0,0,1]
	v_cvt_pk_fp8_f32 v86, v92, v93
	v_cvt_pk_fp8_f32 v87, v96, v97
	v_cvt_pk_fp8_f32 v86, v94, v95 op_sel:[0,0,1]
	v_cvt_pk_fp8_f32 v87, v98, v99 op_sel:[0,0,1]
	v_add_f32_e32 v248, v248, v249
	v_add_f32_e32 v196, v196, v248
	s_lshr_b32 s83, s48, 12
	s_cmp_lg_u32 s83, 0
	s_cbranch_scc1 .Lbm2_Ag2_ks1
	s_lshl_b32 s83, s32, 12
	s_add_u32 s30, s46, s83
	s_addc_u32 s31, s47, 0
	global_load_dwordx4 v[2:5], v79, s[30:31]
	global_load_dwordx4 v[6:9], v79, s[30:31] offset:1024
	global_load_dwordx4 v[12:15], v79, s[30:31] offset:2048
	global_load_dwordx4 v[16:19], v79, s[30:31] offset:3072
.Lbm2_Ag2_ks1:
	s_waitcnt vmcnt(8)
	v_mfma_f32_16x16x32_fp8_fp8 v[132:135], v[36:37], v[84:85], v[132:135]
	v_mfma_f32_16x16x32_fp8_fp8 v[136:139], v[38:39], v[84:85], v[136:139]
	v_mfma_f32_16x16x32_fp8_fp8 v[140:143], v[40:41], v[84:85], v[140:143]
	v_mfma_f32_16x16x32_fp8_fp8 v[144:147], v[42:43], v[84:85], v[144:147]
	v_mfma_f32_16x16x32_fp8_fp8 v[132:135], v[44:45], v[86:87], v[132:135]
	v_mfma_f32_16x16x32_fp8_fp8 v[136:139], v[46:47], v[86:87], v[136:139]
	v_mfma_f32_16x16x32_fp8_fp8 v[140:143], v[48:49], v[86:87], v[140:143]
	v_mfma_f32_16x16x32_fp8_fp8 v[144:147], v[50:51], v[86:87], v[144:147]
	s_branch .Lbm2_Ag2_skip

.Lbm2_Ag2_skip:
	s_bfe_u32 s29, s48, 0x4000c
	s_cmp_eq_u32 s29, 0
	s_cbranch_scc1 .Lbm2_Ag3_skip
	s_waitcnt vmcnt(12)
	v_mfma_f32_16x16x32_fp8_fp8 v[84:87], v[2:3], v[186:187], 0
	v_mfma_f32_16x16x32_fp8_fp8 v[84:87], v[4:5], v[188:189], v[84:87]
	v_mfma_f32_16x16x32_fp8_fp8 v[88:91], v[6:7], v[186:187], 0
	v_mfma_f32_16x16x32_fp8_fp8 v[88:91], v[8:9], v[188:189], v[88:91]
	v_and_b32_e32 v199, s29, v244
	s_cmp_eq_u32 s14, 1
	v_cmp_ne_u32_e32 vcc, 0, v199
	s_cbranch_scc1 .Lbm2_Ag3_near0
	v_add_f32_e32 v200, v81, v193
	v_cndmask_b32_e32 v200, v77, v200, vcc
	s_cmp_eq_u32 s35, 0
	s_cbranch_scc1 .Lbm2_Ag3_first0
	v_mfma_f32_16x16x32_fp8_fp8 v[92:95], v[12:13], v[186:187], 0
	v_mfma_f32_16x16x32_fp8_fp8 v[92:95], v[14:15], v[188:189], v[92:95]
	v_pk_fma_f32 v[84:85], v[84:85], s[16:17], v[200:201] op_sel_hi:[1,1,0]
	v_pk_fma_f32 v[86:87], v[86:87], s[16:17], v[200:201] op_sel_hi:[1,1,0]
	v_mfma_f32_16x16x32_fp8_fp8 v[96:99], v[16:17], v[186:187], 0
	v_mfma_f32_16x16x32_fp8_fp8 v[96:99], v[18:19], v[188:189], v[96:99]
	v_exp_f32_e32 v84, v84
	v_exp_f32_e32 v85, v85
	v_exp_f32_e32 v86, v86
	v_exp_f32_e32 v87, v87
	v_pk_fma_f32 v[88:89], v[88:89], s[16:17], v[200:201] op_sel_hi:[1,1,0]
	v_pk_fma_f32 v[90:91], v[90:91], s[16:17], v[200:201] op_sel_hi:[1,1,0]
	v_exp_f32_e32 v88, v88
	v_exp_f32_e32 v89, v89
	v_exp_f32_e32 v90, v90
	v_exp_f32_e32 v91, v91
	v_pk_fma_f32 v[92:93], v[92:93], s[16:17], v[200:201] op_sel_hi:[1,1,0]
	v_pk_fma_f32 v[94:95], v[94:95], s[16:17], v[200:201] op_sel_hi:[1,1,0]
	v_pk_fma_f32 v[96:97], v[96:97], s[16:17], v[200:201] op_sel_hi:[1,1,0]
	v_pk_fma_f32 v[98:99], v[98:99], s[16:17], v[200:201] op_sel_hi:[1,1,0]
	v_exp_f32_e32 v92, v92
	v_exp_f32_e32 v93, v93
	v_exp_f32_e32 v94, v94
	v_exp_f32_e32 v95, v95
	s_nop 0
	v_exp_f32_e32 v96, v96
	v_exp_f32_e32 v97, v97
	v_exp_f32_e32 v98, v98
	v_exp_f32_e32 v99, v99
	v_pk_add_f32 v[248:249], v[84:85], v[86:87]
	v_pk_add_f32 v[82:83], v[88:89], v[90:91]
	v_pk_add_f32 v[172:173], v[92:93], v[94:95]
	v_pk_add_f32 v[202:203], v[96:97], v[98:99]
	v_cvt_pk_fp8_f32 v84, v84, v85
	v_cvt_pk_fp8_f32 v85, v88, v89
	v_pk_add_f32 v[248:249], v[248:249], v[82:83]
	v_pk_add_f32 v[172:173], v[172:173], v[202:203]
	v_cvt_pk_fp8_f32 v84, v86, v87 op_sel:[0,0,1]
	v_cvt_pk_fp8_f32 v85, v90, v91 op_sel:[0,0,1]
	v_pk_add_f32 v[248:249], v[248:249], v[172:173]
	v_cvt_pk_fp8_f32 v86, v92, v93
	v_cvt_pk_fp8_f32 v87, v96, v97
	v_add_f32_e32 v248, v248, v249
	v_cvt_pk_fp8_f32 v86, v94, v95 op_sel:[0,0,1]
	v_cvt_pk_fp8_f32 v87, v98, v99 op_sel:[0,0,1]
	v_cmp_lt_f32_e32 vcc, 0x43800000, v248
	s_cbranch_vccnz .Lbm2_Ag3_redo
	s_lshl_b32 s83, s32, 12
	s_add_u32 s30, s46, s83
	s_addc_u32 s31, s47, 0
	global_load_dwordx4 v[2:5], v79, s[30:31]
	global_load_dwordx4 v[6:9], v79, s[30:31] offset:1024
	global_load_dwordx4 v[12:15], v79, s[30:31] offset:2048
	global_load_dwordx4 v[16:19], v79, s[30:31] offset:3072
	v_add_f32_e32 v197, v197, v248
	s_waitcnt vmcnt(8)
	v_mfma_f32_16x16x32_fp8_fp8 v[148:151], v[36:37], v[84:85], v[148:151]
	v_mfma_f32_16x16x32_fp8_fp8 v[152:155], v[38:39], v[84:85], v[152:155]
	v_mfma_f32_16x16x32_fp8_fp8 v[156:159], v[40:41], v[84:85], v[156:159]
	v_mfma_f32_16x16x32_fp8_fp8 v[160:163], v[42:43], v[84:85], v[160:163]
	v_mfma_f32_16x16x32_fp8_fp8 v[148:151], v[44:45], v[86:87], v[148:151]
	v_mfma_f32_16x16x32_fp8_fp8 v[152:155], v[46:47], v[86:87], v[152:155]
	v_mfma_f32_16x16x32_fp8_fp8 v[156:159], v[48:49], v[86:87], v[156:159]
	v_mfma_f32_16x16x32_fp8_fp8 v[160:163], v[50:51], v[86:87], v[160:163]
	s_branch .Lbm2_Ag3_skip

.Lbm2_Ag3_exp:
	v_exp_f32_e32 v84, v84
	v_exp_f32_e32 v85, v85
	v_exp_f32_e32 v86, v86
	v_exp_f32_e32 v87, v87
	v_exp_f32_e32 v88, v88
	v_exp_f32_e32 v89, v89
	v_exp_f32_e32 v90, v90
	v_exp_f32_e32 v91, v91
	v_exp_f32_e32 v92, v92
	v_exp_f32_e32 v93, v93
	v_exp_f32_e32 v94, v94
	v_exp_f32_e32 v95, v95
	v_exp_f32_e32 v96, v96
	v_exp_f32_e32 v97, v97
	v_exp_f32_e32 v98, v98
	v_exp_f32_e32 v99, v99
	v_pk_add_f32 v[248:249], v[84:85], v[86:87]
	v_pk_add_f32 v[248:249], v[248:249], v[88:89]
	v_pk_add_f32 v[248:249], v[248:249], v[90:91]
	v_pk_add_f32 v[248:249], v[248:249], v[92:93]
	v_pk_add_f32 v[248:249], v[248:249], v[94:95]
	v_pk_add_f32 v[248:249], v[248:249], v[96:97]
	v_pk_add_f32 v[248:249], v[248:249], v[98:99]
	v_cvt_pk_fp8_f32 v84, v84, v85
	v_cvt_pk_fp8_f32 v85, v88, v89
	v_cvt_pk_fp8_f32 v84, v86, v87 op_sel:[0,0,1]
	v_cvt_pk_fp8_f32 v85, v90, v91 op_sel:[0,0,1]
	v_cvt_pk_fp8_f32 v86, v92, v93
	v_cvt_pk_fp8_f32 v87, v96, v97
	v_cvt_pk_fp8_f32 v86, v94, v95 op_sel:[0,0,1]
	v_cvt_pk_fp8_f32 v87, v98, v99 op_sel:[0,0,1]
	v_add_f32_e32 v248, v248, v249
	v_add_f32_e32 v197, v197, v248
	s_lshl_b32 s83, s32, 12
	s_add_u32 s30, s46, s83
	s_addc_u32 s31, s47, 0
	global_load_dwordx4 v[2:5], v79, s[30:31]
	global_load_dwordx4 v[6:9], v79, s[30:31] offset:1024
	global_load_dwordx4 v[12:15], v79, s[30:31] offset:2048
	global_load_dwordx4 v[16:19], v79, s[30:31] offset:3072
	s_waitcnt vmcnt(8)
	v_mfma_f32_16x16x32_fp8_fp8 v[148:151], v[36:37], v[84:85], v[148:151]
	v_mfma_f32_16x16x32_fp8_fp8 v[152:155], v[38:39], v[84:85], v[152:155]
	v_mfma_f32_16x16x32_fp8_fp8 v[156:159], v[40:41], v[84:85], v[156:159]
	v_mfma_f32_16x16x32_fp8_fp8 v[160:163], v[42:43], v[84:85], v[160:163]
	v_mfma_f32_16x16x32_fp8_fp8 v[148:151], v[44:45], v[86:87], v[148:151]
	v_mfma_f32_16x16x32_fp8_fp8 v[152:155], v[46:47], v[86:87], v[152:155]
	v_mfma_f32_16x16x32_fp8_fp8 v[156:159], v[48:49], v[86:87], v[156:159]
	v_mfma_f32_16x16x32_fp8_fp8 v[160:163], v[50:51], v[86:87], v[160:163]
	s_branch .Lbm2_Ag3_skip

.Lbm2_blkB:
	s_lshl_b32 s12, s15, 12
	s_add_u32 s30, s62, s12
	s_addc_u32 s31, s63, 0
	global_load_dwordx4 v[36:39], v79, s[30:31]
	global_load_dwordx4 v[40:43], v79, s[30:31] offset:1024
	global_load_dwordx4 v[44:47], v79, s[30:31] offset:2048
	global_load_dwordx4 v[48:51], v79, s[30:31] offset:3072
	s_add_i32 s14, s35, 3
	s_add_i32 s13, s25, -1
	s_min_i32 s14, s14, s13
	s_lshl_b32 s13, s14, 2
	s_add_i32 s13, s13, s96
	v_mov_b32_e32 v76, s13
	ds_read_b32 v76, v76 offset:16384
	s_cmp_ge_i32 s54, s21
	s_cselect_b32 s14, 1, 0
	s_bfe_u32 s29, s48, 0x40000
	s_cmp_eq_u32 s29, 0
	s_cbranch_scc1 .Lbm2_Bg0_skip
	s_waitcnt vmcnt(12)
	v_mfma_f32_16x16x32_fp8_fp8 v[84:87], v[20:21], v[164:165], 0
	v_mfma_f32_16x16x32_fp8_fp8 v[84:87], v[22:23], v[166:167], v[84:87]
	v_mfma_f32_16x16x32_fp8_fp8 v[88:91], v[24:25], v[164:165], 0
	v_mfma_f32_16x16x32_fp8_fp8 v[88:91], v[26:27], v[166:167], v[88:91]
	v_and_b32_e32 v199, s29, v244
	s_cmp_eq_u32 s14, 1
	v_cmp_ne_u32_e32 vcc, 0, v199
	s_cbranch_scc1 .Lbm2_Bg0_near0
	v_add_f32_e32 v200, v81, v190
	v_cndmask_b32_e32 v200, v77, v200, vcc
	s_cmp_eq_u32 s35, 0
	s_cbranch_scc1 .Lbm2_Bg0_first0
	v_mfma_f32_16x16x32_fp8_fp8 v[92:95], v[28:29], v[164:165], 0
	v_mfma_f32_16x16x32_fp8_fp8 v[92:95], v[30:31], v[166:167], v[92:95]
	v_pk_fma_f32 v[84:85], v[84:85], s[16:17], v[200:201] op_sel_hi:[1,1,0]
	v_pk_fma_f32 v[86:87], v[86:87], s[16:17], v[200:201] op_sel_hi:[1,1,0]
	v_mfma_f32_16x16x32_fp8_fp8 v[96:99], v[32:33], v[164:165], 0
	v_mfma_f32_16x16x32_fp8_fp8 v[96:99], v[34:35], v[166:167], v[96:99]
	v_exp_f32_e32 v84, v84
	v_exp_f32_e32 v85, v85
	v_exp_f32_e32 v86, v86
	v_exp_f32_e32 v87, v87
	v_pk_fma_f32 v[88:89], v[88:89], s[16:17], v[200:201] op_sel_hi:[1,1,0]
	v_pk_fma_f32 v[90:91], v[90:91], s[16:17], v[200:201] op_sel_hi:[1,1,0]
	v_exp_f32_e32 v88, v88
	v_exp_f32_e32 v89, v89
	v_exp_f32_e32 v90, v90
	v_exp_f32_e32 v91, v91
	v_pk_fma_f32 v[92:93], v[92:93], s[16:17], v[200:201] op_sel_hi:[1,1,0]
	v_pk_fma_f32 v[94:95], v[94:95], s[16:17], v[200:201] op_sel_hi:[1,1,0]
	v_pk_fma_f32 v[96:97], v[96:97], s[16:17], v[200:201] op_sel_hi:[1,1,0]
	v_pk_fma_f32 v[98:99], v[98:99], s[16:17], v[200:201] op_sel_hi:[1,1,0]
	v_exp_f32_e32 v92, v92
	v_exp_f32_e32 v93, v93
	v_exp_f32_e32 v94, v94
	v_exp_f32_e32 v95, v95
	s_nop 0
	v_exp_f32_e32 v96, v96
	v_exp_f32_e32 v97, v97
	v_exp_f32_e32 v98, v98
	v_exp_f32_e32 v99, v99
	v_pk_add_f32 v[248:249], v[84:85], v[86:87]
	v_pk_add_f32 v[82:83], v[88:89], v[90:91]
	v_pk_add_f32 v[172:173], v[92:93], v[94:95]
	v_pk_add_f32 v[202:203], v[96:97], v[98:99]
	v_cvt_pk_fp8_f32 v84, v84, v85
	v_cvt_pk_fp8_f32 v85, v88, v89
	v_pk_add_f32 v[248:249], v[248:249], v[82:83]
	v_pk_add_f32 v[172:173], v[172:173], v[202:203]
	v_cvt_pk_fp8_f32 v84, v86, v87 op_sel:[0,0,1]
	v_cvt_pk_fp8_f32 v85, v90, v91 op_sel:[0,0,1]
	v_pk_add_f32 v[248:249], v[248:249], v[172:173]
	v_cvt_pk_fp8_f32 v86, v92, v93
	v_cvt_pk_fp8_f32 v87, v96, v97
	v_add_f32_e32 v248, v248, v249
	v_cvt_pk_fp8_f32 v86, v94, v95 op_sel:[0,0,1]
	v_cvt_pk_fp8_f32 v87, v98, v99 op_sel:[0,0,1]
	v_cmp_lt_f32_e32 vcc, 0x43800000, v248
	s_cbranch_vccnz .Lbm2_Bg0_redo
	s_lshr_b32 s83, s48, 4
	s_cmp_lg_u32 s83, 0
	s_cbranch_scc1 .Lbm2_Bg0_ks0
	s_lshl_b32 s83, s32, 12
	s_add_u32 s30, s46, s83
	s_addc_u32 s31, s47, 0
	global_load_dwordx4 v[20:23], v79, s[30:31]
	global_load_dwordx4 v[24:27], v79, s[30:31] offset:1024
	global_load_dwordx4 v[28:31], v79, s[30:31] offset:2048
	global_load_dwordx4 v[32:35], v79, s[30:31] offset:3072
.Lbm2_Bg0_ks0:
	v_add_f32_e32 v194, v194, v248
	s_waitcnt vmcnt(8)
	v_mfma_f32_16x16x32_fp8_fp8 v[100:103], v[52:53], v[84:85], v[100:103]
	v_mfma_f32_16x16x32_fp8_fp8 v[104:107], v[54:55], v[84:85], v[104:107]
	v_mfma_f32_16x16x32_fp8_fp8 v[108:111], v[56:57], v[84:85], v[108:111]
	v_mfma_f32_16x16x32_fp8_fp8 v[112:115], v[58:59], v[84:85], v[112:115]
	v_mfma_f32_16x16x32_fp8_fp8 v[100:103], v[60:61], v[86:87], v[100:103]
	v_mfma_f32_16x16x32_fp8_fp8 v[104:107], v[62:63], v[86:87], v[104:107]
	v_mfma_f32_16x16x32_fp8_fp8 v[108:111], v[64:65], v[86:87], v[108:111]
	v_mfma_f32_16x16x32_fp8_fp8 v[112:115], v[66:67], v[86:87], v[112:115]
	s_branch .Lbm2_Bg0_skip

.Lbm2_Bg0_exp:
	v_exp_f32_e32 v84, v84
	v_exp_f32_e32 v85, v85
	v_exp_f32_e32 v86, v86
	v_exp_f32_e32 v87, v87
	v_exp_f32_e32 v88, v88
	v_exp_f32_e32 v89, v89
	v_exp_f32_e32 v90, v90
	v_exp_f32_e32 v91, v91
	v_exp_f32_e32 v92, v92
	v_exp_f32_e32 v93, v93
	v_exp_f32_e32 v94, v94
	v_exp_f32_e32 v95, v95
	v_exp_f32_e32 v96, v96
	v_exp_f32_e32 v97, v97
	v_exp_f32_e32 v98, v98
	v_exp_f32_e32 v99, v99
	v_pk_add_f32 v[248:249], v[84:85], v[86:87]
	v_pk_add_f32 v[248:249], v[248:249], v[88:89]
	v_pk_add_f32 v[248:249], v[248:249], v[90:91]
	v_pk_add_f32 v[248:249], v[248:249], v[92:93]
	v_pk_add_f32 v[248:249], v[248:249], v[94:95]
	v_pk_add_f32 v[248:249], v[248:249], v[96:97]
	v_pk_add_f32 v[248:249], v[248:249], v[98:99]
	v_cvt_pk_fp8_f32 v84, v84, v85
	v_cvt_pk_fp8_f32 v85, v88, v89
	v_cvt_pk_fp8_f32 v84, v86, v87 op_sel:[0,0,1]
	v_cvt_pk_fp8_f32 v85, v90, v91 op_sel:[0,0,1]
	v_cvt_pk_fp8_f32 v86, v92, v93
	v_cvt_pk_fp8_f32 v87, v96, v97
	v_cvt_pk_fp8_f32 v86, v94, v95 op_sel:[0,0,1]
	v_cvt_pk_fp8_f32 v87, v98, v99 op_sel:[0,0,1]
	v_add_f32_e32 v248, v248, v249
	v_add_f32_e32 v194, v194, v248
	s_lshr_b32 s83, s48, 4
	s_cmp_lg_u32 s83, 0
	s_cbranch_scc1 .Lbm2_Bg0_ks1
	s_lshl_b32 s83, s32, 12
	s_add_u32 s30, s46, s83
	s_addc_u32 s31, s47, 0
	global_load_dwordx4 v[20:23], v79, s[30:31]
	global_load_dwordx4 v[24:27], v79, s[30:31] offset:1024
	global_load_dwordx4 v[28:31], v79, s[30:31] offset:2048
	global_load_dwordx4 v[32:35], v79, s[30:31] offset:3072
.Lbm2_Bg0_ks1:
	s_waitcnt vmcnt(8)
	v_mfma_f32_16x16x32_fp8_fp8 v[100:103], v[52:53], v[84:85], v[100:103]
	v_mfma_f32_16x16x32_fp8_fp8 v[104:107], v[54:55], v[84:85], v[104:107]
	v_mfma_f32_16x16x32_fp8_fp8 v[108:111], v[56:57], v[84:85], v[108:111]
	v_mfma_f32_16x16x32_fp8_fp8 v[112:115], v[58:59], v[84:85], v[112:115]
	v_mfma_f32_16x16x32_fp8_fp8 v[100:103], v[60:61], v[86:87], v[100:103]
	v_mfma_f32_16x16x32_fp8_fp8 v[104:107], v[62:63], v[86:87], v[104:107]
	v_mfma_f32_16x16x32_fp8_fp8 v[108:111], v[64:65], v[86:87], v[108:111]
	v_mfma_f32_16x16x32_fp8_fp8 v[112:115], v[66:67], v[86:87], v[112:115]
	s_branch .Lbm2_Bg0_skip

.Lbm2_Bg0_skip:
	s_bfe_u32 s29, s48, 0x40004
	s_cmp_eq_u32 s29, 0
	s_cbranch_scc1 .Lbm2_Bg1_skip
	s_waitcnt vmcnt(12)
	v_mfma_f32_16x16x32_fp8_fp8 v[84:87], v[20:21], v[168:169], 0
	v_mfma_f32_16x16x32_fp8_fp8 v[84:87], v[22:23], v[170:171], v[84:87]
	v_mfma_f32_16x16x32_fp8_fp8 v[88:91], v[24:25], v[168:169], 0
	v_mfma_f32_16x16x32_fp8_fp8 v[88:91], v[26:27], v[170:171], v[88:91]
	v_and_b32_e32 v199, s29, v244
	s_cmp_eq_u32 s14, 1
	v_cmp_ne_u32_e32 vcc, 0, v199
	s_cbranch_scc1 .Lbm2_Bg1_near0
	v_add_f32_e32 v200, v81, v191
	v_cndmask_b32_e32 v200, v77, v200, vcc
	s_cmp_eq_u32 s35, 0
	s_cbranch_scc1 .Lbm2_Bg1_first0
	v_mfma_f32_16x16x32_fp8_fp8 v[92:95], v[28:29], v[168:169], 0
	v_mfma_f32_16x16x32_fp8_fp8 v[92:95], v[30:31], v[170:171], v[92:95]
	v_pk_fma_f32 v[84:85], v[84:85], s[16:17], v[200:201] op_sel_hi:[1,1,0]
	v_pk_fma_f32 v[86:87], v[86:87], s[16:17], v[200:201] op_sel_hi:[1,1,0]
	v_mfma_f32_16x16x32_fp8_fp8 v[96:99], v[32:33], v[168:169], 0
	v_mfma_f32_16x16x32_fp8_fp8 v[96:99], v[34:35], v[170:171], v[96:99]
	v_exp_f32_e32 v84, v84
	v_exp_f32_e32 v85, v85
	v_exp_f32_e32 v86, v86
	v_exp_f32_e32 v87, v87
	v_pk_fma_f32 v[88:89], v[88:89], s[16:17], v[200:201] op_sel_hi:[1,1,0]
	v_pk_fma_f32 v[90:91], v[90:91], s[16:17], v[200:201] op_sel_hi:[1,1,0]
	v_exp_f32_e32 v88, v88
	v_exp_f32_e32 v89, v89
	v_exp_f32_e32 v90, v90
	v_exp_f32_e32 v91, v91
	v_pk_fma_f32 v[92:93], v[92:93], s[16:17], v[200:201] op_sel_hi:[1,1,0]
	v_pk_fma_f32 v[94:95], v[94:95], s[16:17], v[200:201] op_sel_hi:[1,1,0]
	v_pk_fma_f32 v[96:97], v[96:97], s[16:17], v[200:201] op_sel_hi:[1,1,0]
	v_pk_fma_f32 v[98:99], v[98:99], s[16:17], v[200:201] op_sel_hi:[1,1,0]
	v_exp_f32_e32 v92, v92
	v_exp_f32_e32 v93, v93
	v_exp_f32_e32 v94, v94
	v_exp_f32_e32 v95, v95
	s_nop 0
	v_exp_f32_e32 v96, v96
	v_exp_f32_e32 v97, v97
	v_exp_f32_e32 v98, v98
	v_exp_f32_e32 v99, v99
	v_pk_add_f32 v[248:249], v[84:85], v[86:87]
	v_pk_add_f32 v[82:83], v[88:89], v[90:91]
	v_pk_add_f32 v[172:173], v[92:93], v[94:95]
	v_pk_add_f32 v[202:203], v[96:97], v[98:99]
	v_cvt_pk_fp8_f32 v84, v84, v85
	v_cvt_pk_fp8_f32 v85, v88, v89
	v_pk_add_f32 v[248:249], v[248:249], v[82:83]
	v_pk_add_f32 v[172:173], v[172:173], v[202:203]
	v_cvt_pk_fp8_f32 v84, v86, v87 op_sel:[0,0,1]
	v_cvt_pk_fp8_f32 v85, v90, v91 op_sel:[0,0,1]
	v_pk_add_f32 v[248:249], v[248:249], v[172:173]
	v_cvt_pk_fp8_f32 v86, v92, v93
	v_cvt_pk_fp8_f32 v87, v96, v97
	v_add_f32_e32 v248, v248, v249
	v_cvt_pk_fp8_f32 v86, v94, v95 op_sel:[0,0,1]
	v_cvt_pk_fp8_f32 v87, v98, v99 op_sel:[0,0,1]
	v_cmp_lt_f32_e32 vcc, 0x43800000, v248
	s_cbranch_vccnz .Lbm2_Bg1_redo
	s_lshr_b32 s83, s48, 8
	s_cmp_lg_u32 s83, 0
	s_cbranch_scc1 .Lbm2_Bg1_ks0
	s_lshl_b32 s83, s32, 12
	s_add_u32 s30, s46, s83
	s_addc_u32 s31, s47, 0
	global_load_dwordx4 v[20:23], v79, s[30:31]
	global_load_dwordx4 v[24:27], v79, s[30:31] offset:1024
	global_load_dwordx4 v[28:31], v79, s[30:31] offset:2048
	global_load_dwordx4 v[32:35], v79, s[30:31] offset:3072
.Lbm2_Bg1_ks0:
	v_add_f32_e32 v195, v195, v248
	s_waitcnt vmcnt(8)
	v_mfma_f32_16x16x32_fp8_fp8 v[116:119], v[52:53], v[84:85], v[116:119]
	v_mfma_f32_16x16x32_fp8_fp8 v[120:123], v[54:55], v[84:85], v[120:123]
	v_mfma_f32_16x16x32_fp8_fp8 v[124:127], v[56:57], v[84:85], v[124:127]
	v_mfma_f32_16x16x32_fp8_fp8 v[128:131], v[58:59], v[84:85], v[128:131]
	v_mfma_f32_16x16x32_fp8_fp8 v[116:119], v[60:61], v[86:87], v[116:119]
	v_mfma_f32_16x16x32_fp8_fp8 v[120:123], v[62:63], v[86:87], v[120:123]
	v_mfma_f32_16x16x32_fp8_fp8 v[124:127], v[64:65], v[86:87], v[124:127]
	v_mfma_f32_16x16x32_fp8_fp8 v[128:131], v[66:67], v[86:87], v[128:131]
	s_branch .Lbm2_Bg1_skip

.Lbm2_Bg1_exp:
	v_exp_f32_e32 v84, v84
	v_exp_f32_e32 v85, v85
	v_exp_f32_e32 v86, v86
	v_exp_f32_e32 v87, v87
	v_exp_f32_e32 v88, v88
	v_exp_f32_e32 v89, v89
	v_exp_f32_e32 v90, v90
	v_exp_f32_e32 v91, v91
	v_exp_f32_e32 v92, v92
	v_exp_f32_e32 v93, v93
	v_exp_f32_e32 v94, v94
	v_exp_f32_e32 v95, v95
	v_exp_f32_e32 v96, v96
	v_exp_f32_e32 v97, v97
	v_exp_f32_e32 v98, v98
	v_exp_f32_e32 v99, v99
	v_pk_add_f32 v[248:249], v[84:85], v[86:87]
	v_pk_add_f32 v[248:249], v[248:249], v[88:89]
	v_pk_add_f32 v[248:249], v[248:249], v[90:91]
	v_pk_add_f32 v[248:249], v[248:249], v[92:93]
	v_pk_add_f32 v[248:249], v[248:249], v[94:95]
	v_pk_add_f32 v[248:249], v[248:249], v[96:97]
	v_pk_add_f32 v[248:249], v[248:249], v[98:99]
	v_cvt_pk_fp8_f32 v84, v84, v85
	v_cvt_pk_fp8_f32 v85, v88, v89
	v_cvt_pk_fp8_f32 v84, v86, v87 op_sel:[0,0,1]
	v_cvt_pk_fp8_f32 v85, v90, v91 op_sel:[0,0,1]
	v_cvt_pk_fp8_f32 v86, v92, v93
	v_cvt_pk_fp8_f32 v87, v96, v97
	v_cvt_pk_fp8_f32 v86, v94, v95 op_sel:[0,0,1]
	v_cvt_pk_fp8_f32 v87, v98, v99 op_sel:[0,0,1]
	v_add_f32_e32 v248, v248, v249
	v_add_f32_e32 v195, v195, v248
	s_lshr_b32 s83, s48, 8
	s_cmp_lg_u32 s83, 0
	s_cbranch_scc1 .Lbm2_Bg1_ks1
	s_lshl_b32 s83, s32, 12
	s_add_u32 s30, s46, s83
	s_addc_u32 s31, s47, 0
	global_load_dwordx4 v[20:23], v79, s[30:31]
	global_load_dwordx4 v[24:27], v79, s[30:31] offset:1024
	global_load_dwordx4 v[28:31], v79, s[30:31] offset:2048
	global_load_dwordx4 v[32:35], v79, s[30:31] offset:3072
.Lbm2_Bg1_ks1:
	s_waitcnt vmcnt(8)
	v_mfma_f32_16x16x32_fp8_fp8 v[116:119], v[52:53], v[84:85], v[116:119]
	v_mfma_f32_16x16x32_fp8_fp8 v[120:123], v[54:55], v[84:85], v[120:123]
	v_mfma_f32_16x16x32_fp8_fp8 v[124:127], v[56:57], v[84:85], v[124:127]
	v_mfma_f32_16x16x32_fp8_fp8 v[128:131], v[58:59], v[84:85], v[128:131]
	v_mfma_f32_16x16x32_fp8_fp8 v[116:119], v[60:61], v[86:87], v[116:119]
	v_mfma_f32_16x16x32_fp8_fp8 v[120:123], v[62:63], v[86:87], v[120:123]
	v_mfma_f32_16x16x32_fp8_fp8 v[124:127], v[64:65], v[86:87], v[124:127]
	v_mfma_f32_16x16x32_fp8_fp8 v[128:131], v[66:67], v[86:87], v[128:131]
	s_branch .Lbm2_Bg1_skip

.Lbm2_Bg1_skip:
	s_bfe_u32 s29, s48, 0x40008
	s_cmp_eq_u32 s29, 0
	s_cbranch_scc1 .Lbm2_Bg2_skip
	s_waitcnt vmcnt(12)
	v_mfma_f32_16x16x32_fp8_fp8 v[84:87], v[20:21], v[182:183], 0
	v_mfma_f32_16x16x32_fp8_fp8 v[84:87], v[22:23], v[184:185], v[84:87]
	v_mfma_f32_16x16x32_fp8_fp8 v[88:91], v[24:25], v[182:183], 0
	v_mfma_f32_16x16x32_fp8_fp8 v[88:91], v[26:27], v[184:185], v[88:91]
	v_and_b32_e32 v199, s29, v244
	s_cmp_eq_u32 s14, 1
	v_cmp_ne_u32_e32 vcc, 0, v199
	s_cbranch_scc1 .Lbm2_Bg2_near0
	v_add_f32_e32 v200, v81, v192
	v_cndmask_b32_e32 v200, v77, v200, vcc
	s_cmp_eq_u32 s35, 0
	s_cbranch_scc1 .Lbm2_Bg2_first0
	v_mfma_f32_16x16x32_fp8_fp8 v[92:95], v[28:29], v[182:183], 0
	v_mfma_f32_16x16x32_fp8_fp8 v[92:95], v[30:31], v[184:185], v[92:95]
	v_pk_fma_f32 v[84:85], v[84:85], s[16:17], v[200:201] op_sel_hi:[1,1,0]
	v_pk_fma_f32 v[86:87], v[86:87], s[16:17], v[200:201] op_sel_hi:[1,1,0]
	v_mfma_f32_16x16x32_fp8_fp8 v[96:99], v[32:33], v[182:183], 0
	v_mfma_f32_16x16x32_fp8_fp8 v[96:99], v[34:35], v[184:185], v[96:99]
	v_exp_f32_e32 v84, v84
	v_exp_f32_e32 v85, v85
	v_exp_f32_e32 v86, v86
	v_exp_f32_e32 v87, v87
	v_pk_fma_f32 v[88:89], v[88:89], s[16:17], v[200:201] op_sel_hi:[1,1,0]
	v_pk_fma_f32 v[90:91], v[90:91], s[16:17], v[200:201] op_sel_hi:[1,1,0]
	v_exp_f32_e32 v88, v88
	v_exp_f32_e32 v89, v89
	v_exp_f32_e32 v90, v90
	v_exp_f32_e32 v91, v91
	v_pk_fma_f32 v[92:93], v[92:93], s[16:17], v[200:201] op_sel_hi:[1,1,0]
	v_pk_fma_f32 v[94:95], v[94:95], s[16:17], v[200:201] op_sel_hi:[1,1,0]
	v_pk_fma_f32 v[96:97], v[96:97], s[16:17], v[200:201] op_sel_hi:[1,1,0]
	v_pk_fma_f32 v[98:99], v[98:99], s[16:17], v[200:201] op_sel_hi:[1,1,0]
	v_exp_f32_e32 v92, v92
	v_exp_f32_e32 v93, v93
	v_exp_f32_e32 v94, v94
	v_exp_f32_e32 v95, v95
	s_nop 0
	v_exp_f32_e32 v96, v96
	v_exp_f32_e32 v97, v97
	v_exp_f32_e32 v98, v98
	v_exp_f32_e32 v99, v99
	v_pk_add_f32 v[248:249], v[84:85], v[86:87]
	v_pk_add_f32 v[82:83], v[88:89], v[90:91]
	v_pk_add_f32 v[172:173], v[92:93], v[94:95]
	v_pk_add_f32 v[202:203], v[96:97], v[98:99]
	v_cvt_pk_fp8_f32 v84, v84, v85
	v_cvt_pk_fp8_f32 v85, v88, v89
	v_pk_add_f32 v[248:249], v[248:249], v[82:83]
	v_pk_add_f32 v[172:173], v[172:173], v[202:203]
	v_cvt_pk_fp8_f32 v84, v86, v87 op_sel:[0,0,1]
	v_cvt_pk_fp8_f32 v85, v90, v91 op_sel:[0,0,1]
	v_pk_add_f32 v[248:249], v[248:249], v[172:173]
	v_cvt_pk_fp8_f32 v86, v92, v93
	v_cvt_pk_fp8_f32 v87, v96, v97
	v_add_f32_e32 v248, v248, v249
	v_cvt_pk_fp8_f32 v86, v94, v95 op_sel:[0,0,1]
	v_cvt_pk_fp8_f32 v87, v98, v99 op_sel:[0,0,1]
	v_cmp_lt_f32_e32 vcc, 0x43800000, v248
	s_cbranch_vccnz .Lbm2_Bg2_redo
	s_lshr_b32 s83, s48, 12
	s_cmp_lg_u32 s83, 0
	s_cbranch_scc1 .Lbm2_Bg2_ks0
	s_lshl_b32 s83, s32, 12
	s_add_u32 s30, s46, s83
	s_addc_u32 s31, s47, 0
	global_load_dwordx4 v[20:23], v79, s[30:31]
	global_load_dwordx4 v[24:27], v79, s[30:31] offset:1024
	global_load_dwordx4 v[28:31], v79, s[30:31] offset:2048
	global_load_dwordx4 v[32:35], v79, s[30:31] offset:3072
.Lbm2_Bg2_ks0:
	v_add_f32_e32 v196, v196, v248
	s_waitcnt vmcnt(8)
	v_mfma_f32_16x16x32_fp8_fp8 v[132:135], v[52:53], v[84:85], v[132:135]
	v_mfma_f32_16x16x32_fp8_fp8 v[136:139], v[54:55], v[84:85], v[136:139]
	v_mfma_f32_16x16x32_fp8_fp8 v[140:143], v[56:57], v[84:85], v[140:143]
	v_mfma_f32_16x16x32_fp8_fp8 v[144:147], v[58:59], v[84:85], v[144:147]
	v_mfma_f32_16x16x32_fp8_fp8 v[132:135], v[60:61], v[86:87], v[132:135]
	v_mfma_f32_16x16x32_fp8_fp8 v[136:139], v[62:63], v[86:87], v[136:139]
	v_mfma_f32_16x16x32_fp8_fp8 v[140:143], v[64:65], v[86:87], v[140:143]
	v_mfma_f32_16x16x32_fp8_fp8 v[144:147], v[66:67], v[86:87], v[144:147]
	s_branch .Lbm2_Bg2_skip

.Lbm2_Bg2_exp:
	v_exp_f32_e32 v84, v84
	v_exp_f32_e32 v85, v85
	v_exp_f32_e32 v86, v86
	v_exp_f32_e32 v87, v87
	v_exp_f32_e32 v88, v88
	v_exp_f32_e32 v89, v89
	v_exp_f32_e32 v90, v90
	v_exp_f32_e32 v91, v91
	v_exp_f32_e32 v92, v92
	v_exp_f32_e32 v93, v93
	v_exp_f32_e32 v94, v94
	v_exp_f32_e32 v95, v95
	v_exp_f32_e32 v96, v96
	v_exp_f32_e32 v97, v97
	v_exp_f32_e32 v98, v98
	v_exp_f32_e32 v99, v99
	v_pk_add_f32 v[248:249], v[84:85], v[86:87]
	v_pk_add_f32 v[248:249], v[248:249], v[88:89]
	v_pk_add_f32 v[248:249], v[248:249], v[90:91]
	v_pk_add_f32 v[248:249], v[248:249], v[92:93]
	v_pk_add_f32 v[248:249], v[248:249], v[94:95]
	v_pk_add_f32 v[248:249], v[248:249], v[96:97]
	v_pk_add_f32 v[248:249], v[248:249], v[98:99]
	v_cvt_pk_fp8_f32 v84, v84, v85
	v_cvt_pk_fp8_f32 v85, v88, v89
	v_cvt_pk_fp8_f32 v84, v86, v87 op_sel:[0,0,1]
	v_cvt_pk_fp8_f32 v85, v90, v91 op_sel:[0,0,1]
	v_cvt_pk_fp8_f32 v86, v92, v93
	v_cvt_pk_fp8_f32 v87, v96, v97
	v_cvt_pk_fp8_f32 v86, v94, v95 op_sel:[0,0,1]
	v_cvt_pk_fp8_f32 v87, v98, v99 op_sel:[0,0,1]
	v_add_f32_e32 v248, v248, v249
	v_add_f32_e32 v196, v196, v248
	s_lshr_b32 s83, s48, 12
	s_cmp_lg_u32 s83, 0
	s_cbranch_scc1 .Lbm2_Bg2_ks1
	s_lshl_b32 s83, s32, 12
	s_add_u32 s30, s46, s83
	s_addc_u32 s31, s47, 0
	global_load_dwordx4 v[20:23], v79, s[30:31]
	global_load_dwordx4 v[24:27], v79, s[30:31] offset:1024
	global_load_dwordx4 v[28:31], v79, s[30:31] offset:2048
	global_load_dwordx4 v[32:35], v79, s[30:31] offset:3072
.Lbm2_Bg2_ks1:
	s_waitcnt vmcnt(8)
	v_mfma_f32_16x16x32_fp8_fp8 v[132:135], v[52:53], v[84:85], v[132:135]
	v_mfma_f32_16x16x32_fp8_fp8 v[136:139], v[54:55], v[84:85], v[136:139]
	v_mfma_f32_16x16x32_fp8_fp8 v[140:143], v[56:57], v[84:85], v[140:143]
	v_mfma_f32_16x16x32_fp8_fp8 v[144:147], v[58:59], v[84:85], v[144:147]
	v_mfma_f32_16x16x32_fp8_fp8 v[132:135], v[60:61], v[86:87], v[132:135]
	v_mfma_f32_16x16x32_fp8_fp8 v[136:139], v[62:63], v[86:87], v[136:139]
	v_mfma_f32_16x16x32_fp8_fp8 v[140:143], v[64:65], v[86:87], v[140:143]
	v_mfma_f32_16x16x32_fp8_fp8 v[144:147], v[66:67], v[86:87], v[144:147]
	s_branch .Lbm2_Bg2_skip

.Lbm2_Bg2_skip:
	s_bfe_u32 s29, s48, 0x4000c
	s_cmp_eq_u32 s29, 0
	s_cbranch_scc1 .Lbm2_Bg3_skip
	s_waitcnt vmcnt(12)
	v_mfma_f32_16x16x32_fp8_fp8 v[84:87], v[20:21], v[186:187], 0
	v_mfma_f32_16x16x32_fp8_fp8 v[84:87], v[22:23], v[188:189], v[84:87]
	v_mfma_f32_16x16x32_fp8_fp8 v[88:91], v[24:25], v[186:187], 0
	v_mfma_f32_16x16x32_fp8_fp8 v[88:91], v[26:27], v[188:189], v[88:91]
	v_and_b32_e32 v199, s29, v244
	s_cmp_eq_u32 s14, 1
	v_cmp_ne_u32_e32 vcc, 0, v199
	s_cbranch_scc1 .Lbm2_Bg3_near0
	v_add_f32_e32 v200, v81, v193
	v_cndmask_b32_e32 v200, v77, v200, vcc
	s_cmp_eq_u32 s35, 0
	s_cbranch_scc1 .Lbm2_Bg3_first0
	v_mfma_f32_16x16x32_fp8_fp8 v[92:95], v[28:29], v[186:187], 0
	v_mfma_f32_16x16x32_fp8_fp8 v[92:95], v[30:31], v[188:189], v[92:95]
	v_pk_fma_f32 v[84:85], v[84:85], s[16:17], v[200:201] op_sel_hi:[1,1,0]
	v_pk_fma_f32 v[86:87], v[86:87], s[16:17], v[200:201] op_sel_hi:[1,1,0]
	v_mfma_f32_16x16x32_fp8_fp8 v[96:99], v[32:33], v[186:187], 0
	v_mfma_f32_16x16x32_fp8_fp8 v[96:99], v[34:35], v[188:189], v[96:99]
	v_exp_f32_e32 v84, v84
	v_exp_f32_e32 v85, v85
	v_exp_f32_e32 v86, v86
	v_exp_f32_e32 v87, v87
	v_pk_fma_f32 v[88:89], v[88:89], s[16:17], v[200:201] op_sel_hi:[1,1,0]
	v_pk_fma_f32 v[90:91], v[90:91], s[16:17], v[200:201] op_sel_hi:[1,1,0]
	v_exp_f32_e32 v88, v88
	v_exp_f32_e32 v89, v89
	v_exp_f32_e32 v90, v90
	v_exp_f32_e32 v91, v91
	v_pk_fma_f32 v[92:93], v[92:93], s[16:17], v[200:201] op_sel_hi:[1,1,0]
	v_pk_fma_f32 v[94:95], v[94:95], s[16:17], v[200:201] op_sel_hi:[1,1,0]
	v_pk_fma_f32 v[96:97], v[96:97], s[16:17], v[200:201] op_sel_hi:[1,1,0]
	v_pk_fma_f32 v[98:99], v[98:99], s[16:17], v[200:201] op_sel_hi:[1,1,0]
	v_exp_f32_e32 v92, v92
	v_exp_f32_e32 v93, v93
	v_exp_f32_e32 v94, v94
	v_exp_f32_e32 v95, v95
	s_nop 0
	v_exp_f32_e32 v96, v96
	v_exp_f32_e32 v97, v97
	v_exp_f32_e32 v98, v98
	v_exp_f32_e32 v99, v99
	v_pk_add_f32 v[248:249], v[84:85], v[86:87]
	v_pk_add_f32 v[82:83], v[88:89], v[90:91]
	v_pk_add_f32 v[172:173], v[92:93], v[94:95]
	v_pk_add_f32 v[202:203], v[96:97], v[98:99]
	v_cvt_pk_fp8_f32 v84, v84, v85
	v_cvt_pk_fp8_f32 v85, v88, v89
	v_pk_add_f32 v[248:249], v[248:249], v[82:83]
	v_pk_add_f32 v[172:173], v[172:173], v[202:203]
	v_cvt_pk_fp8_f32 v84, v86, v87 op_sel:[0,0,1]
	v_cvt_pk_fp8_f32 v85, v90, v91 op_sel:[0,0,1]
	v_pk_add_f32 v[248:249], v[248:249], v[172:173]
	v_cvt_pk_fp8_f32 v86, v92, v93
	v_cvt_pk_fp8_f32 v87, v96, v97
	v_add_f32_e32 v248, v248, v249
	v_cvt_pk_fp8_f32 v86, v94, v95 op_sel:[0,0,1]
	v_cvt_pk_fp8_f32 v87, v98, v99 op_sel:[0,0,1]
	v_cmp_lt_f32_e32 vcc, 0x43800000, v248
	s_cbranch_vccnz .Lbm2_Bg3_redo
	s_lshl_b32 s83, s32, 12
	s_add_u32 s30, s46, s83
	s_addc_u32 s31, s47, 0
	global_load_dwordx4 v[20:23], v79, s[30:31]
	global_load_dwordx4 v[24:27], v79, s[30:31] offset:1024
	global_load_dwordx4 v[28:31], v79, s[30:31] offset:2048
	global_load_dwordx4 v[32:35], v79, s[30:31] offset:3072
	v_add_f32_e32 v197, v197, v248
	s_waitcnt vmcnt(8)
	v_mfma_f32_16x16x32_fp8_fp8 v[148:151], v[52:53], v[84:85], v[148:151]
	v_mfma_f32_16x16x32_fp8_fp8 v[152:155], v[54:55], v[84:85], v[152:155]
	v_mfma_f32_16x16x32_fp8_fp8 v[156:159], v[56:57], v[84:85], v[156:159]
	v_mfma_f32_16x16x32_fp8_fp8 v[160:163], v[58:59], v[84:85], v[160:163]
	v_mfma_f32_16x16x32_fp8_fp8 v[148:151], v[60:61], v[86:87], v[148:151]
	v_mfma_f32_16x16x32_fp8_fp8 v[152:155], v[62:63], v[86:87], v[152:155]
	v_mfma_f32_16x16x32_fp8_fp8 v[156:159], v[64:65], v[86:87], v[156:159]
	v_mfma_f32_16x16x32_fp8_fp8 v[160:163], v[66:67], v[86:87], v[160:163]
	s_branch .Lbm2_Bg3_skip

.Lbm2_Bg3_exp:
	v_exp_f32_e32 v84, v84
	v_exp_f32_e32 v85, v85
	v_exp_f32_e32 v86, v86
	v_exp_f32_e32 v87, v87
	v_exp_f32_e32 v88, v88
	v_exp_f32_e32 v89, v89
	v_exp_f32_e32 v90, v90
	v_exp_f32_e32 v91, v91
	v_exp_f32_e32 v92, v92
	v_exp_f32_e32 v93, v93
	v_exp_f32_e32 v94, v94
	v_exp_f32_e32 v95, v95
	v_exp_f32_e32 v96, v96
	v_exp_f32_e32 v97, v97
	v_exp_f32_e32 v98, v98
	v_exp_f32_e32 v99, v99
	v_pk_add_f32 v[248:249], v[84:85], v[86:87]
	v_pk_add_f32 v[248:249], v[248:249], v[88:89]
	v_pk_add_f32 v[248:249], v[248:249], v[90:91]
	v_pk_add_f32 v[248:249], v[248:249], v[92:93]
	v_pk_add_f32 v[248:249], v[248:249], v[94:95]
	v_pk_add_f32 v[248:249], v[248:249], v[96:97]
	v_pk_add_f32 v[248:249], v[248:249], v[98:99]
	v_cvt_pk_fp8_f32 v84, v84, v85
	v_cvt_pk_fp8_f32 v85, v88, v89
	v_cvt_pk_fp8_f32 v84, v86, v87 op_sel:[0,0,1]
	v_cvt_pk_fp8_f32 v85, v90, v91 op_sel:[0,0,1]
	v_cvt_pk_fp8_f32 v86, v92, v93
	v_cvt_pk_fp8_f32 v87, v96, v97
	v_cvt_pk_fp8_f32 v86, v94, v95 op_sel:[0,0,1]
	v_cvt_pk_fp8_f32 v87, v98, v99 op_sel:[0,0,1]
	v_add_f32_e32 v248, v248, v249
	v_add_f32_e32 v197, v197, v248
	s_lshl_b32 s83, s32, 12
	s_add_u32 s30, s46, s83
	s_addc_u32 s31, s47, 0
	global_load_dwordx4 v[20:23], v79, s[30:31]
	global_load_dwordx4 v[24:27], v79, s[30:31] offset:1024
	global_load_dwordx4 v[28:31], v79, s[30:31] offset:2048
	global_load_dwordx4 v[32:35], v79, s[30:31] offset:3072
	s_waitcnt vmcnt(8)
	v_mfma_f32_16x16x32_fp8_fp8 v[148:151], v[52:53], v[84:85], v[148:151]
	v_mfma_f32_16x16x32_fp8_fp8 v[152:155], v[54:55], v[84:85], v[152:155]
	v_mfma_f32_16x16x32_fp8_fp8 v[156:159], v[56:57], v[84:85], v[156:159]
	v_mfma_f32_16x16x32_fp8_fp8 v[160:163], v[58:59], v[84:85], v[160:163]
	v_mfma_f32_16x16x32_fp8_fp8 v[148:151], v[60:61], v[86:87], v[148:151]
	v_mfma_f32_16x16x32_fp8_fp8 v[152:155], v[62:63], v[86:87], v[152:155]
	v_mfma_f32_16x16x32_fp8_fp8 v[156:159], v[64:65], v[86:87], v[156:159]
	v_mfma_f32_16x16x32_fp8_fp8 v[160:163], v[66:67], v[86:87], v[160:163]
	s_branch .Lbm2_Bg3_skip

.LBB0_2049:
.LBB0_2050:
	v_readfirstlane_b32 s40, v70
	v_readfirstlane_b32 s41, v71
	v_readfirstlane_b32 s62, v72
	v_readfirstlane_b32 s63, v73
	v_and_b32_e32 v248, 15, v181
	v_lshrrev_b32_e32 v249, 4, v181
	v_lshrrev_b32_e32 v248, 2, v248
	v_lshlrev_b32_e32 v249, 2, v249
	v_readlane_b32 s23, v243, 32
	v_mov_b32_e32 v244, 1
	v_lshlrev_b32_e32 v244, v248, v244
	s_mov_b32 s10, 0x3e38aa3b
	s_mov_b32 s11, 0x3e38aa3b
	v_lshlrev_b32_e32 v79, 4, v181
	s_add_i32 s23, s23, s47
	v_add_u32_e32 v247, s23, v248
	v_mad_u64_u32 v[250:251], s[6:7], v247, v212, v[68:69]
	global_load_dwordx4 v[100:103], v[250:251], off
	global_load_dwordx4 v[104:107], v[250:251], off offset:64
	v_add_u32_e32 v249, 4, v247
	v_mad_u64_u32 v[250:251], s[6:7], v249, v212, v[68:69]
	global_load_dwordx4 v[108:111], v[250:251], off
	global_load_dwordx4 v[112:115], v[250:251], off offset:64
	v_add_u32_e32 v249, 8, v247
	v_mad_u64_u32 v[250:251], s[6:7], v249, v212, v[68:69]
	global_load_dwordx4 v[116:119], v[250:251], off
	global_load_dwordx4 v[120:123], v[250:251], off offset:64
	v_add_u32_e32 v249, 12, v247
	v_mad_u64_u32 v[250:251], s[6:7], v249, v212, v[68:69]
	global_load_dwordx4 v[124:127], v[250:251], off
	global_load_dwordx4 v[128:131], v[250:251], off offset:64
	v_and_b32_e32 v248, 15, v181
	v_lshrrev_b32_e32 v249, 4, v181
	v_lshlrev_b32_e32 v198, 6, v248
	v_lshl_add_u32 v198, v249, 2, v198
	v_add_u32_e32 v198, s46, v198
	v_lshl_add_u32 v199, v248, 2, s46
	ds_read_b32 v12, v198 offset:16384
	ds_read_b32 v13, v198 offset:16400
	ds_read_b32 v14, v198 offset:16416
	ds_read_b32 v15, v198 offset:16432
	ds_read_b32 v16, v199 offset:17408
	v_lshl_add_u32 v199, v181, 2, s46
	v_mov_b32_e32 v17, 1
	v_lshlrev_b32_e32 v17, v248, v17
	s_waitcnt lgkmcnt(0)
	v_mul_f32_e32 v81, 0x3fb8aa3b, v81
	ds_write_b32 v199, v11 offset:16384
	ds_write_b32 v199, v11 offset:16640
	ds_write_b32 v199, v11 offset:16896
	ds_write_b32 v199, v11 offset:17152
	v_cmp_lt_i32_e32 vcc, v249, v16
	v_and_b32_e32 v12, 0xff, v12
	v_lshl_add_u32 v12, v12, 2, s46
	v_cndmask_b32_e32 v18, 0, v17, vcc
	ds_or_b32 v12, v18 offset:16384
	v_add_u32_e32 v18, 4, v249
	v_cmp_lt_i32_e32 vcc, v18, v16
	v_and_b32_e32 v13, 0xff, v13
	v_lshl_add_u32 v13, v13, 2, s46
	v_cndmask_b32_e32 v18, 0, v17, vcc
	ds_or_b32 v13, v18 offset:16384
	v_add_u32_e32 v18, 8, v249
	v_cmp_lt_i32_e32 vcc, v18, v16
	v_and_b32_e32 v14, 0xff, v14
	v_lshl_add_u32 v14, v14, 2, s46
	v_cndmask_b32_e32 v18, 0, v17, vcc
	ds_or_b32 v14, v18 offset:16384
	v_add_u32_e32 v18, 12, v249
	v_cmp_lt_i32_e32 vcc, v18, v16
	v_and_b32_e32 v15, 0xff, v15
	v_lshl_add_u32 v15, v15, 2, s46
	v_cndmask_b32_e32 v18, 0, v17, vcc
	ds_or_b32 v15, v18 offset:16384
	s_waitcnt lgkmcnt(0)
	ds_read_b32 v12, v199 offset:16384
	ds_read_b32 v13, v199 offset:16640
	ds_read_b32 v14, v199 offset:16896
	ds_read_b32 v15, v199 offset:17152
	s_mov_b32 s25, 0
	s_waitcnt lgkmcnt(0)
	v_cmp_ne_u32_e64 s[4:5], 0, v12
	v_lshlrev_b32_e32 v16, 16, v12
	v_add_u32_e32 v17, 0, v181
	v_or_b32_e32 v16, v16, v17
	v_mbcnt_lo_u32_b32 v17, s4, 0
	v_mbcnt_hi_u32_b32 v17, s5, v17
	v_add_u32_e32 v17, s25, v17
	v_lshl_add_u32 v17, v17, 2, s46
	v_add_u32_e32 v17, 0x4000, v17
	v_add_u32_e32 v18, 0x4400, v199
	s_bcnt1_i32_b64 s9, s[4:5]
	v_cndmask_b32_e64 v17, v18, v17, s[4:5]
	s_add_i32 s25, s25, s9
	ds_write_b32 v17, v16
	v_cmp_ne_u32_e64 s[4:5], 0, v13
	v_lshlrev_b32_e32 v16, 16, v13
	v_add_u32_e32 v17, 64, v181
	v_or_b32_e32 v16, v16, v17
	v_mbcnt_lo_u32_b32 v17, s4, 0
	v_mbcnt_hi_u32_b32 v17, s5, v17
	v_add_u32_e32 v17, s25, v17
	v_lshl_add_u32 v17, v17, 2, s46
	v_add_u32_e32 v17, 0x4000, v17
	v_add_u32_e32 v18, 0x4400, v199
	s_bcnt1_i32_b64 s9, s[4:5]
	v_cndmask_b32_e64 v17, v18, v17, s[4:5]
	s_add_i32 s25, s25, s9
	ds_write_b32 v17, v16
	v_cmp_ne_u32_e64 s[4:5], 0, v14
	v_lshlrev_b32_e32 v16, 16, v14
	v_add_u32_e32 v17, 128, v181
	v_or_b32_e32 v16, v16, v17
	v_mbcnt_lo_u32_b32 v17, s4, 0
	v_mbcnt_hi_u32_b32 v17, s5, v17
	v_add_u32_e32 v17, s25, v17
	v_lshl_add_u32 v17, v17, 2, s46
	v_add_u32_e32 v17, 0x4000, v17
	v_add_u32_e32 v18, 0x4400, v199
	s_bcnt1_i32_b64 s9, s[4:5]
	v_cndmask_b32_e64 v17, v18, v17, s[4:5]
	s_add_i32 s25, s25, s9
	ds_write_b32 v17, v16
	v_cmp_ne_u32_e64 s[4:5], 0, v15
	v_lshlrev_b32_e32 v16, 16, v15
	v_add_u32_e32 v17, 192, v181
	v_or_b32_e32 v16, v16, v17
	v_mbcnt_lo_u32_b32 v17, s4, 0
	v_mbcnt_hi_u32_b32 v17, s5, v17
	v_add_u32_e32 v17, s25, v17
	v_lshl_add_u32 v17, v17, 2, s46
	v_add_u32_e32 v17, 0x4000, v17
	v_add_u32_e32 v18, 0x4400, v199
	s_bcnt1_i32_b64 s9, s[4:5]
	v_cndmask_b32_e64 v17, v18, v17, s[4:5]
	s_add_i32 s25, s25, s9
	ds_write_b32 v17, v16
	s_waitcnt vmcnt(0)
	v_lshlrev_b32_e32 v245, 16, v100
	v_and_b32_e32 v246, 0xffff0000, v100
	v_mul_f32_e32 v245, 0x41000000, v245
	v_mul_f32_e32 v246, 0x41000000, v246
	v_lshlrev_b32_e32 v248, 16, v101
	v_and_b32_e32 v249, 0xffff0000, v101
	v_cvt_pk_fp8_f32 v164, v245, v246
	v_mul_f32_e32 v248, 0x41000000, v248
	v_mul_f32_e32 v249, 0x41000000, v249
	s_nop 0
	v_cvt_pk_fp8_f32 v164, v248, v249 op_sel:[0,0,1]
	v_lshlrev_b32_e32 v245, 16, v102
	v_and_b32_e32 v246, 0xffff0000, v102
	v_mul_f32_e32 v245, 0x41000000, v245
	v_mul_f32_e32 v246, 0x41000000, v246
	v_lshlrev_b32_e32 v248, 16, v103
	v_and_b32_e32 v249, 0xffff0000, v103
	v_cvt_pk_fp8_f32 v165, v245, v246
	v_mul_f32_e32 v248, 0x41000000, v248
	v_mul_f32_e32 v249, 0x41000000, v249
	s_nop 0
	v_cvt_pk_fp8_f32 v165, v248, v249 op_sel:[0,0,1]
	v_lshlrev_b32_e32 v245, 16, v104
	v_and_b32_e32 v246, 0xffff0000, v104
	v_mul_f32_e32 v245, 0x41000000, v245
	v_mul_f32_e32 v246, 0x41000000, v246
	v_lshlrev_b32_e32 v248, 16, v105
	v_and_b32_e32 v249, 0xffff0000, v105
	v_cvt_pk_fp8_f32 v166, v245, v246
	v_mul_f32_e32 v248, 0x41000000, v248
	v_mul_f32_e32 v249, 0x41000000, v249
	s_nop 0
	v_cvt_pk_fp8_f32 v166, v248, v249 op_sel:[0,0,1]
	v_lshlrev_b32_e32 v245, 16, v106
	v_and_b32_e32 v246, 0xffff0000, v106
	v_mul_f32_e32 v245, 0x41000000, v245
	v_mul_f32_e32 v246, 0x41000000, v246
	v_lshlrev_b32_e32 v248, 16, v107
	v_and_b32_e32 v249, 0xffff0000, v107
	v_cvt_pk_fp8_f32 v167, v245, v246
	v_mul_f32_e32 v248, 0x41000000, v248
	v_mul_f32_e32 v249, 0x41000000, v249
	s_nop 0
	v_cvt_pk_fp8_f32 v167, v248, v249 op_sel:[0,0,1]
	v_lshlrev_b32_e32 v245, 16, v108
	v_and_b32_e32 v246, 0xffff0000, v108
	v_mul_f32_e32 v245, 0x41000000, v245
	v_mul_f32_e32 v246, 0x41000000, v246
	v_lshlrev_b32_e32 v248, 16, v109
	v_and_b32_e32 v249, 0xffff0000, v109
	v_cvt_pk_fp8_f32 v168, v245, v246
	v_mul_f32_e32 v248, 0x41000000, v248
	v_mul_f32_e32 v249, 0x41000000, v249
	s_nop 0
	v_cvt_pk_fp8_f32 v168, v248, v249 op_sel:[0,0,1]
	v_lshlrev_b32_e32 v245, 16, v110
	v_and_b32_e32 v246, 0xffff0000, v110
	v_mul_f32_e32 v245, 0x41000000, v245
	v_mul_f32_e32 v246, 0x41000000, v246
	v_lshlrev_b32_e32 v248, 16, v111
	v_and_b32_e32 v249, 0xffff0000, v111
	v_cvt_pk_fp8_f32 v169, v245, v246
	v_mul_f32_e32 v248, 0x41000000, v248
	v_mul_f32_e32 v249, 0x41000000, v249
	s_nop 0
	v_cvt_pk_fp8_f32 v169, v248, v249 op_sel:[0,0,1]
	v_lshlrev_b32_e32 v245, 16, v112
	v_and_b32_e32 v246, 0xffff0000, v112
	v_mul_f32_e32 v245, 0x41000000, v245
	v_mul_f32_e32 v246, 0x41000000, v246
	v_lshlrev_b32_e32 v248, 16, v113
	v_and_b32_e32 v249, 0xffff0000, v113
	v_cvt_pk_fp8_f32 v170, v245, v246
	v_mul_f32_e32 v248, 0x41000000, v248
	v_mul_f32_e32 v249, 0x41000000, v249
	s_nop 0
	v_cvt_pk_fp8_f32 v170, v248, v249 op_sel:[0,0,1]
	v_lshlrev_b32_e32 v245, 16, v114
	v_and_b32_e32 v246, 0xffff0000, v114
	v_mul_f32_e32 v245, 0x41000000, v245
	v_mul_f32_e32 v246, 0x41000000, v246
	v_lshlrev_b32_e32 v248, 16, v115
	v_and_b32_e32 v249, 0xffff0000, v115
	v_cvt_pk_fp8_f32 v171, v245, v246
	v_mul_f32_e32 v248, 0x41000000, v248
	v_mul_f32_e32 v249, 0x41000000, v249
	s_nop 0
	v_cvt_pk_fp8_f32 v171, v248, v249 op_sel:[0,0,1]
	v_lshlrev_b32_e32 v245, 16, v116
	v_and_b32_e32 v246, 0xffff0000, v116
	v_mul_f32_e32 v245, 0x41000000, v245
	v_mul_f32_e32 v246, 0x41000000, v246
	v_lshlrev_b32_e32 v248, 16, v117
	v_and_b32_e32 v249, 0xffff0000, v117
	v_cvt_pk_fp8_f32 v182, v245, v246
	v_mul_f32_e32 v248, 0x41000000, v248
	v_mul_f32_e32 v249, 0x41000000, v249
	s_nop 0
	v_cvt_pk_fp8_f32 v182, v248, v249 op_sel:[0,0,1]
	v_lshlrev_b32_e32 v245, 16, v118
	v_and_b32_e32 v246, 0xffff0000, v118
	v_mul_f32_e32 v245, 0x41000000, v245
	v_mul_f32_e32 v246, 0x41000000, v246
	v_lshlrev_b32_e32 v248, 16, v119
	v_and_b32_e32 v249, 0xffff0000, v119
	v_cvt_pk_fp8_f32 v183, v245, v246
	v_mul_f32_e32 v248, 0x41000000, v248
	v_mul_f32_e32 v249, 0x41000000, v249
	s_nop 0
	v_cvt_pk_fp8_f32 v183, v248, v249 op_sel:[0,0,1]
	v_lshlrev_b32_e32 v245, 16, v120
	v_and_b32_e32 v246, 0xffff0000, v120
	v_mul_f32_e32 v245, 0x41000000, v245
	v_mul_f32_e32 v246, 0x41000000, v246
	v_lshlrev_b32_e32 v248, 16, v121
	v_and_b32_e32 v249, 0xffff0000, v121
	v_cvt_pk_fp8_f32 v184, v245, v246
	v_mul_f32_e32 v248, 0x41000000, v248
	v_mul_f32_e32 v249, 0x41000000, v249
	s_nop 0
	v_cvt_pk_fp8_f32 v184, v248, v249 op_sel:[0,0,1]
	v_lshlrev_b32_e32 v245, 16, v122
	v_and_b32_e32 v246, 0xffff0000, v122
	v_mul_f32_e32 v245, 0x41000000, v245
	v_mul_f32_e32 v246, 0x41000000, v246
	v_lshlrev_b32_e32 v248, 16, v123
	v_and_b32_e32 v249, 0xffff0000, v123
	v_cvt_pk_fp8_f32 v185, v245, v246
	v_mul_f32_e32 v248, 0x41000000, v248
	v_mul_f32_e32 v249, 0x41000000, v249
	s_nop 0
	v_cvt_pk_fp8_f32 v185, v248, v249 op_sel:[0,0,1]
	v_lshlrev_b32_e32 v245, 16, v124
	v_and_b32_e32 v246, 0xffff0000, v124
	v_mul_f32_e32 v245, 0x41000000, v245
	v_mul_f32_e32 v246, 0x41000000, v246
	v_lshlrev_b32_e32 v248, 16, v125
	v_and_b32_e32 v249, 0xffff0000, v125
	v_cvt_pk_fp8_f32 v186, v245, v246
	v_mul_f32_e32 v248, 0x41000000, v248
	v_mul_f32_e32 v249, 0x41000000, v249
	s_nop 0
	v_cvt_pk_fp8_f32 v186, v248, v249 op_sel:[0,0,1]
	v_lshlrev_b32_e32 v245, 16, v126
	v_and_b32_e32 v246, 0xffff0000, v126
	v_mul_f32_e32 v245, 0x41000000, v245
	v_mul_f32_e32 v246, 0x41000000, v246
	v_lshlrev_b32_e32 v248, 16, v127
	v_and_b32_e32 v249, 0xffff0000, v127
	v_cvt_pk_fp8_f32 v187, v245, v246
	v_mul_f32_e32 v248, 0x41000000, v248
	v_mul_f32_e32 v249, 0x41000000, v249
	s_nop 0
	v_cvt_pk_fp8_f32 v187, v248, v249 op_sel:[0,0,1]
	v_lshlrev_b32_e32 v245, 16, v128
	v_and_b32_e32 v246, 0xffff0000, v128
	v_mul_f32_e32 v245, 0x41000000, v245
	v_mul_f32_e32 v246, 0x41000000, v246
	v_lshlrev_b32_e32 v248, 16, v129
	v_and_b32_e32 v249, 0xffff0000, v129
	v_cvt_pk_fp8_f32 v188, v245, v246
	v_mul_f32_e32 v248, 0x41000000, v248
	v_mul_f32_e32 v249, 0x41000000, v249
	s_nop 0
	v_cvt_pk_fp8_f32 v188, v248, v249 op_sel:[0,0,1]
	v_lshlrev_b32_e32 v245, 16, v130
	v_and_b32_e32 v246, 0xffff0000, v130
	v_mul_f32_e32 v245, 0x41000000, v245
	v_mul_f32_e32 v246, 0x41000000, v246
	v_lshlrev_b32_e32 v248, 16, v131
	v_and_b32_e32 v249, 0xffff0000, v131
	v_cvt_pk_fp8_f32 v189, v245, v246
	v_mul_f32_e32 v248, 0x41000000, v248
	v_mul_f32_e32 v249, 0x41000000, v249
	s_nop 0
	v_cvt_pk_fp8_f32 v189, v248, v249 op_sel:[0,0,1]
	v_mov_b64_e32 v[100:101], 0
	v_mov_b64_e32 v[102:103], 0
	v_mov_b64_e32 v[104:105], 0
	v_mov_b64_e32 v[106:107], 0
	v_mov_b64_e32 v[108:109], 0
	v_mov_b64_e32 v[110:111], 0
	v_mov_b64_e32 v[112:113], 0
	v_mov_b64_e32 v[114:115], 0
	v_mov_b32_e32 v190, 0
	v_mov_b32_e32 v194, 0
	v_mov_b64_e32 v[116:117], 0
	v_mov_b64_e32 v[118:119], 0
	v_mov_b64_e32 v[120:121], 0
	v_mov_b64_e32 v[122:123], 0
	v_mov_b64_e32 v[124:125], 0
	v_mov_b64_e32 v[126:127], 0
	v_mov_b64_e32 v[128:129], 0
	v_mov_b64_e32 v[130:131], 0
	v_mov_b32_e32 v191, 0
	v_mov_b32_e32 v195, 0
	v_mov_b64_e32 v[132:133], 0
	v_mov_b64_e32 v[134:135], 0
	v_mov_b64_e32 v[136:137], 0
	v_mov_b64_e32 v[138:139], 0
	v_mov_b64_e32 v[140:141], 0
	v_mov_b64_e32 v[142:143], 0
	v_mov_b64_e32 v[144:145], 0
	v_mov_b64_e32 v[146:147], 0
	v_mov_b32_e32 v192, 0
	v_mov_b32_e32 v196, 0
	v_mov_b64_e32 v[148:149], 0
	v_mov_b64_e32 v[150:151], 0
	v_mov_b64_e32 v[152:153], 0
	v_mov_b64_e32 v[154:155], 0
	v_mov_b64_e32 v[156:157], 0
	v_mov_b64_e32 v[158:159], 0
	v_mov_b64_e32 v[160:161], 0
	v_mov_b64_e32 v[162:163], 0
	v_mov_b32_e32 v193, 0
	v_mov_b32_e32 v197, 0
	v_mov_b32_e32 v77, 0xff800000
	v_mov_b32_e32 v78, 0xff800000
	s_waitcnt lgkmcnt(0)
	s_mov_b32 s35, 0
	s_lshl_b32 s9, s35, 2
	s_add_i32 s9, s9, s46
	v_mov_b32_e32 v76, s9
	ds_read_b32 v76, v76 offset:16384
	s_add_i32 s50, s25, -1
	s_min_i32 s50, s50, 1
	s_waitcnt lgkmcnt(0)
	v_readfirstlane_b32 s9, v76
	s_and_b32 s38, s9, 0xffff
	s_lshr_b32 s48, s9, 16
	s_lshl_b32 s9, s50, 2
	s_add_i32 s9, s9, s46
	v_mov_b32_e32 v76, s9
	ds_read_b32 v76, v76 offset:16384
	s_lshl_b32 s29, s38, 12
	s_add_u32 s30, s40, s29
	s_addc_u32 s31, s41, 0
	global_load_dwordx4 v[2:5], v79, s[30:31]
	global_load_dwordx4 v[6:9], v79, s[30:31] offset:1024
	global_load_dwordx4 v[12:15], v79, s[30:31] offset:2048
	global_load_dwordx4 v[16:19], v79, s[30:31] offset:3072
	s_lshl_b32 s29, s38, 12
	s_add_u32 s30, s62, s29
	s_addc_u32 s31, s63, 0
	global_load_dwordx4 v[36:39], v79, s[30:31]
	global_load_dwordx4 v[40:43], v79, s[30:31] offset:1024
	global_load_dwordx4 v[44:47], v79, s[30:31] offset:2048
	global_load_dwordx4 v[48:51], v79, s[30:31] offset:3072
	s_waitcnt lgkmcnt(0)
	v_readfirstlane_b32 s9, v76
	s_and_b32 s27, s9, 0xffff
	s_lshr_b32 s8, s9, 16
	s_add_i32 s83, s25, -1
	s_min_i32 s83, s83, 2
	s_lshl_b32 s83, s83, 2
	s_add_i32 s83, s83, s46
	v_mov_b32_e32 v76, s83
	ds_read_b32 v76, v76 offset:16384
	s_lshl_b32 s83, s27, 12
	s_add_u32 s30, s40, s83
	s_addc_u32 s31, s41, 0
	global_load_dwordx4 v[20:23], v79, s[30:31]
	global_load_dwordx4 v[24:27], v79, s[30:31] offset:1024
	global_load_dwordx4 v[28:31], v79, s[30:31] offset:2048
	global_load_dwordx4 v[32:35], v79, s[30:31] offset:3072
	s_waitcnt lgkmcnt(0)
	v_readfirstlane_b32 s9, v76
	s_and_b32 s32, s9, 0xffff
	s_lshr_b32 s55, s9, 16
	v_readfirstlane_b32 s83, v1
	s_bitcmp1_b32 s83, 8
	s_cbranch_scc0 .Lbm3_nostag
	s_sleep 4
.Lbm3_nostag:
.Lbm3_blkA:
	s_lshl_b32 s29, s27, 12
	s_add_u32 s30, s62, s29
	s_addc_u32 s31, s63, 0
	global_load_dwordx4 v[52:55], v79, s[30:31]
	global_load_dwordx4 v[56:59], v79, s[30:31] offset:1024
	global_load_dwordx4 v[60:63], v79, s[30:31] offset:2048
	global_load_dwordx4 v[64:67], v79, s[30:31] offset:3072
	s_add_i32 s50, s35, 3
	s_add_i32 s9, s25, -1
	s_min_i32 s50, s50, s9
	s_lshl_b32 s9, s50, 2
	s_add_i32 s9, s9, s46
	v_mov_b32_e32 v76, s9
	ds_read_b32 v76, v76 offset:16384
	s_cmp_ge_i32 s38, s21
	s_cselect_b32 s50, 1, 0
	s_bfe_u32 s29, s48, 0x40000
	s_cmp_eq_u32 s29, 0
	s_cbranch_scc1 .Lbm3_Ag0_skip
	s_waitcnt vmcnt(12)
	v_mfma_f32_16x16x32_fp8_fp8 v[84:87], v[2:3], v[164:165], 0
	v_mfma_f32_16x16x32_fp8_fp8 v[84:87], v[4:5], v[166:167], v[84:87]
	v_mfma_f32_16x16x32_fp8_fp8 v[88:91], v[6:7], v[164:165], 0
	v_mfma_f32_16x16x32_fp8_fp8 v[88:91], v[8:9], v[166:167], v[88:91]
	v_and_b32_e32 v199, s29, v244
	s_cmp_eq_u32 s50, 1
	v_cmp_ne_u32_e32 vcc, 0, v199
	s_cbranch_scc1 .Lbm3_Ag0_near0
	v_add_f32_e32 v200, v81, v190
	v_cndmask_b32_e32 v200, v77, v200, vcc
	s_cmp_eq_u32 s35, 0
	s_cbranch_scc1 .Lbm3_Ag0_first0
	v_mfma_f32_16x16x32_fp8_fp8 v[92:95], v[12:13], v[164:165], 0
	v_mfma_f32_16x16x32_fp8_fp8 v[92:95], v[14:15], v[166:167], v[92:95]
	v_pk_fma_f32 v[84:85], v[84:85], s[10:11], v[200:201] op_sel_hi:[1,1,0]
	v_pk_fma_f32 v[86:87], v[86:87], s[10:11], v[200:201] op_sel_hi:[1,1,0]
	v_mfma_f32_16x16x32_fp8_fp8 v[96:99], v[16:17], v[164:165], 0
	v_mfma_f32_16x16x32_fp8_fp8 v[96:99], v[18:19], v[166:167], v[96:99]
	v_exp_f32_e32 v84, v84
	v_exp_f32_e32 v85, v85
	v_exp_f32_e32 v86, v86
	v_exp_f32_e32 v87, v87
	v_pk_fma_f32 v[88:89], v[88:89], s[10:11], v[200:201] op_sel_hi:[1,1,0]
	v_pk_fma_f32 v[90:91], v[90:91], s[10:11], v[200:201] op_sel_hi:[1,1,0]
	v_exp_f32_e32 v88, v88
	v_exp_f32_e32 v89, v89
	v_exp_f32_e32 v90, v90
	v_exp_f32_e32 v91, v91
	v_pk_fma_f32 v[92:93], v[92:93], s[10:11], v[200:201] op_sel_hi:[1,1,0]
	v_pk_fma_f32 v[94:95], v[94:95], s[10:11], v[200:201] op_sel_hi:[1,1,0]
	v_pk_fma_f32 v[96:97], v[96:97], s[10:11], v[200:201] op_sel_hi:[1,1,0]
	v_pk_fma_f32 v[98:99], v[98:99], s[10:11], v[200:201] op_sel_hi:[1,1,0]
	v_exp_f32_e32 v92, v92
	v_exp_f32_e32 v93, v93
	v_exp_f32_e32 v94, v94
	v_exp_f32_e32 v95, v95
	s_nop 0
	v_exp_f32_e32 v96, v96
	v_exp_f32_e32 v97, v97
	v_exp_f32_e32 v98, v98
	v_exp_f32_e32 v99, v99
	v_pk_add_f32 v[248:249], v[84:85], v[86:87]
	v_pk_add_f32 v[82:83], v[88:89], v[90:91]
	v_pk_add_f32 v[172:173], v[92:93], v[94:95]
	v_pk_add_f32 v[202:203], v[96:97], v[98:99]
	v_cvt_pk_fp8_f32 v84, v84, v85
	v_cvt_pk_fp8_f32 v85, v88, v89
	v_pk_add_f32 v[248:249], v[248:249], v[82:83]
	v_pk_add_f32 v[172:173], v[172:173], v[202:203]
	v_cvt_pk_fp8_f32 v84, v86, v87 op_sel:[0,0,1]
	v_cvt_pk_fp8_f32 v85, v90, v91 op_sel:[0,0,1]
	v_pk_add_f32 v[248:249], v[248:249], v[172:173]
	v_cvt_pk_fp8_f32 v86, v92, v93
	v_cvt_pk_fp8_f32 v87, v96, v97
	v_add_f32_e32 v248, v248, v249
	v_cvt_pk_fp8_f32 v86, v94, v95 op_sel:[0,0,1]
	v_cvt_pk_fp8_f32 v87, v98, v99 op_sel:[0,0,1]
	v_cmp_lt_f32_e32 vcc, 0x43800000, v248
	s_cbranch_vccnz .Lbm3_Ag0_redo
	s_lshr_b32 s83, s48, 4
	s_cmp_lg_u32 s83, 0
	s_cbranch_scc1 .Lbm3_Ag0_ks0
	s_lshl_b32 s83, s32, 12
	s_add_u32 s30, s40, s83
	s_addc_u32 s31, s41, 0
	global_load_dwordx4 v[2:5], v79, s[30:31]
	global_load_dwordx4 v[6:9], v79, s[30:31] offset:1024
	global_load_dwordx4 v[12:15], v79, s[30:31] offset:2048
	global_load_dwordx4 v[16:19], v79, s[30:31] offset:3072

.Lbm3_Ag0_exp:
	v_exp_f32_e32 v84, v84
	v_exp_f32_e32 v85, v85
	v_exp_f32_e32 v86, v86
	v_exp_f32_e32 v87, v87
	v_exp_f32_e32 v88, v88
	v_exp_f32_e32 v89, v89
	v_exp_f32_e32 v90, v90
	v_exp_f32_e32 v91, v91
	v_exp_f32_e32 v92, v92
	v_exp_f32_e32 v93, v93
	v_exp_f32_e32 v94, v94
	v_exp_f32_e32 v95, v95
	v_exp_f32_e32 v96, v96
	v_exp_f32_e32 v97, v97
	v_exp_f32_e32 v98, v98
	v_exp_f32_e32 v99, v99
	v_pk_add_f32 v[248:249], v[84:85], v[86:87]
	v_pk_add_f32 v[248:249], v[248:249], v[88:89]
	v_pk_add_f32 v[248:249], v[248:249], v[90:91]
	v_pk_add_f32 v[248:249], v[248:249], v[92:93]
	v_pk_add_f32 v[248:249], v[248:249], v[94:95]
	v_pk_add_f32 v[248:249], v[248:249], v[96:97]
	v_pk_add_f32 v[248:249], v[248:249], v[98:99]
	v_cvt_pk_fp8_f32 v84, v84, v85
	v_cvt_pk_fp8_f32 v85, v88, v89
	v_cvt_pk_fp8_f32 v84, v86, v87 op_sel:[0,0,1]
	v_cvt_pk_fp8_f32 v85, v90, v91 op_sel:[0,0,1]
	v_cvt_pk_fp8_f32 v86, v92, v93
	v_cvt_pk_fp8_f32 v87, v96, v97
	v_cvt_pk_fp8_f32 v86, v94, v95 op_sel:[0,0,1]
	v_cvt_pk_fp8_f32 v87, v98, v99 op_sel:[0,0,1]
	v_add_f32_e32 v248, v248, v249
	v_add_f32_e32 v194, v194, v248
	s_lshr_b32 s83, s48, 4
	s_cmp_lg_u32 s83, 0
	s_cbranch_scc1 .Lbm3_Ag0_ks1
	s_lshl_b32 s83, s32, 12
	s_add_u32 s30, s40, s83
	s_addc_u32 s31, s41, 0
	global_load_dwordx4 v[2:5], v79, s[30:31]
	global_load_dwordx4 v[6:9], v79, s[30:31] offset:1024
	global_load_dwordx4 v[12:15], v79, s[30:31] offset:2048
	global_load_dwordx4 v[16:19], v79, s[30:31] offset:3072

.Lbm3_Ag0_skip:
	s_bfe_u32 s29, s48, 0x40004
	s_cmp_eq_u32 s29, 0
	s_cbranch_scc1 .Lbm3_Ag1_skip
	s_waitcnt vmcnt(12)
	v_mfma_f32_16x16x32_fp8_fp8 v[84:87], v[2:3], v[168:169], 0
	v_mfma_f32_16x16x32_fp8_fp8 v[84:87], v[4:5], v[170:171], v[84:87]
	v_mfma_f32_16x16x32_fp8_fp8 v[88:91], v[6:7], v[168:169], 0
	v_mfma_f32_16x16x32_fp8_fp8 v[88:91], v[8:9], v[170:171], v[88:91]
	v_and_b32_e32 v199, s29, v244
	s_cmp_eq_u32 s50, 1
	v_cmp_ne_u32_e32 vcc, 0, v199
	s_cbranch_scc1 .Lbm3_Ag1_near0
	v_add_f32_e32 v200, v81, v191
	v_cndmask_b32_e32 v200, v77, v200, vcc
	s_cmp_eq_u32 s35, 0
	s_cbranch_scc1 .Lbm3_Ag1_first0
	v_mfma_f32_16x16x32_fp8_fp8 v[92:95], v[12:13], v[168:169], 0
	v_mfma_f32_16x16x32_fp8_fp8 v[92:95], v[14:15], v[170:171], v[92:95]
	v_pk_fma_f32 v[84:85], v[84:85], s[10:11], v[200:201] op_sel_hi:[1,1,0]
	v_pk_fma_f32 v[86:87], v[86:87], s[10:11], v[200:201] op_sel_hi:[1,1,0]
	v_mfma_f32_16x16x32_fp8_fp8 v[96:99], v[16:17], v[168:169], 0
	v_mfma_f32_16x16x32_fp8_fp8 v[96:99], v[18:19], v[170:171], v[96:99]
	v_exp_f32_e32 v84, v84
	v_exp_f32_e32 v85, v85
	v_exp_f32_e32 v86, v86
	v_exp_f32_e32 v87, v87
	v_pk_fma_f32 v[88:89], v[88:89], s[10:11], v[200:201] op_sel_hi:[1,1,0]
	v_pk_fma_f32 v[90:91], v[90:91], s[10:11], v[200:201] op_sel_hi:[1,1,0]
	v_exp_f32_e32 v88, v88
	v_exp_f32_e32 v89, v89
	v_exp_f32_e32 v90, v90
	v_exp_f32_e32 v91, v91
	v_pk_fma_f32 v[92:93], v[92:93], s[10:11], v[200:201] op_sel_hi:[1,1,0]
	v_pk_fma_f32 v[94:95], v[94:95], s[10:11], v[200:201] op_sel_hi:[1,1,0]
	v_pk_fma_f32 v[96:97], v[96:97], s[10:11], v[200:201] op_sel_hi:[1,1,0]
	v_pk_fma_f32 v[98:99], v[98:99], s[10:11], v[200:201] op_sel_hi:[1,1,0]
	v_exp_f32_e32 v92, v92
	v_exp_f32_e32 v93, v93
	v_exp_f32_e32 v94, v94
	v_exp_f32_e32 v95, v95
	s_nop 0
	v_exp_f32_e32 v96, v96
	v_exp_f32_e32 v97, v97
	v_exp_f32_e32 v98, v98
	v_exp_f32_e32 v99, v99
	v_pk_add_f32 v[248:249], v[84:85], v[86:87]
	v_pk_add_f32 v[82:83], v[88:89], v[90:91]
	v_pk_add_f32 v[172:173], v[92:93], v[94:95]
	v_pk_add_f32 v[202:203], v[96:97], v[98:99]
	v_cvt_pk_fp8_f32 v84, v84, v85
	v_cvt_pk_fp8_f32 v85, v88, v89
	v_pk_add_f32 v[248:249], v[248:249], v[82:83]
	v_pk_add_f32 v[172:173], v[172:173], v[202:203]
	v_cvt_pk_fp8_f32 v84, v86, v87 op_sel:[0,0,1]
	v_cvt_pk_fp8_f32 v85, v90, v91 op_sel:[0,0,1]
	v_pk_add_f32 v[248:249], v[248:249], v[172:173]
	v_cvt_pk_fp8_f32 v86, v92, v93
	v_cvt_pk_fp8_f32 v87, v96, v97
	v_add_f32_e32 v248, v248, v249
	v_cvt_pk_fp8_f32 v86, v94, v95 op_sel:[0,0,1]
	v_cvt_pk_fp8_f32 v87, v98, v99 op_sel:[0,0,1]
	v_cmp_lt_f32_e32 vcc, 0x43800000, v248
	s_cbranch_vccnz .Lbm3_Ag1_redo
	s_lshr_b32 s83, s48, 8
	s_cmp_lg_u32 s83, 0
	s_cbranch_scc1 .Lbm3_Ag1_ks0
	s_lshl_b32 s83, s32, 12
	s_add_u32 s30, s40, s83
	s_addc_u32 s31, s41, 0
	global_load_dwordx4 v[2:5], v79, s[30:31]
	global_load_dwordx4 v[6:9], v79, s[30:31] offset:1024
	global_load_dwordx4 v[12:15], v79, s[30:31] offset:2048
	global_load_dwordx4 v[16:19], v79, s[30:31] offset:3072

.Lbm3_Ag1_exp:
	v_exp_f32_e32 v84, v84
	v_exp_f32_e32 v85, v85
	v_exp_f32_e32 v86, v86
	v_exp_f32_e32 v87, v87
	v_exp_f32_e32 v88, v88
	v_exp_f32_e32 v89, v89
	v_exp_f32_e32 v90, v90
	v_exp_f32_e32 v91, v91
	v_exp_f32_e32 v92, v92
	v_exp_f32_e32 v93, v93
	v_exp_f32_e32 v94, v94
	v_exp_f32_e32 v95, v95
	v_exp_f32_e32 v96, v96
	v_exp_f32_e32 v97, v97
	v_exp_f32_e32 v98, v98
	v_exp_f32_e32 v99, v99
	v_pk_add_f32 v[248:249], v[84:85], v[86:87]
	v_pk_add_f32 v[248:249], v[248:249], v[88:89]
	v_pk_add_f32 v[248:249], v[248:249], v[90:91]
	v_pk_add_f32 v[248:249], v[248:249], v[92:93]
	v_pk_add_f32 v[248:249], v[248:249], v[94:95]
	v_pk_add_f32 v[248:249], v[248:249], v[96:97]
	v_pk_add_f32 v[248:249], v[248:249], v[98:99]
	v_cvt_pk_fp8_f32 v84, v84, v85
	v_cvt_pk_fp8_f32 v85, v88, v89
	v_cvt_pk_fp8_f32 v84, v86, v87 op_sel:[0,0,1]
	v_cvt_pk_fp8_f32 v85, v90, v91 op_sel:[0,0,1]
	v_cvt_pk_fp8_f32 v86, v92, v93
	v_cvt_pk_fp8_f32 v87, v96, v97
	v_cvt_pk_fp8_f32 v86, v94, v95 op_sel:[0,0,1]
	v_cvt_pk_fp8_f32 v87, v98, v99 op_sel:[0,0,1]
	v_add_f32_e32 v248, v248, v249
	v_add_f32_e32 v195, v195, v248
	s_lshr_b32 s83, s48, 8
	s_cmp_lg_u32 s83, 0
	s_cbranch_scc1 .Lbm3_Ag1_ks1
	s_lshl_b32 s83, s32, 12
	s_add_u32 s30, s40, s83
	s_addc_u32 s31, s41, 0
	global_load_dwordx4 v[2:5], v79, s[30:31]
	global_load_dwordx4 v[6:9], v79, s[30:31] offset:1024
	global_load_dwordx4 v[12:15], v79, s[30:31] offset:2048
	global_load_dwordx4 v[16:19], v79, s[30:31] offset:3072

.Lbm3_Ag1_skip:
	s_bfe_u32 s29, s48, 0x40008
	s_cmp_eq_u32 s29, 0
	s_cbranch_scc1 .Lbm3_Ag2_skip
	s_waitcnt vmcnt(12)
	v_mfma_f32_16x16x32_fp8_fp8 v[84:87], v[2:3], v[182:183], 0
	v_mfma_f32_16x16x32_fp8_fp8 v[84:87], v[4:5], v[184:185], v[84:87]
	v_mfma_f32_16x16x32_fp8_fp8 v[88:91], v[6:7], v[182:183], 0
	v_mfma_f32_16x16x32_fp8_fp8 v[88:91], v[8:9], v[184:185], v[88:91]
	v_and_b32_e32 v199, s29, v244
	s_cmp_eq_u32 s50, 1
	v_cmp_ne_u32_e32 vcc, 0, v199
	s_cbranch_scc1 .Lbm3_Ag2_near0
	v_add_f32_e32 v200, v81, v192
	v_cndmask_b32_e32 v200, v77, v200, vcc
	s_cmp_eq_u32 s35, 0
	s_cbranch_scc1 .Lbm3_Ag2_first0
	v_mfma_f32_16x16x32_fp8_fp8 v[92:95], v[12:13], v[182:183], 0
	v_mfma_f32_16x16x32_fp8_fp8 v[92:95], v[14:15], v[184:185], v[92:95]
	v_pk_fma_f32 v[84:85], v[84:85], s[10:11], v[200:201] op_sel_hi:[1,1,0]
	v_pk_fma_f32 v[86:87], v[86:87], s[10:11], v[200:201] op_sel_hi:[1,1,0]
	v_mfma_f32_16x16x32_fp8_fp8 v[96:99], v[16:17], v[182:183], 0
	v_mfma_f32_16x16x32_fp8_fp8 v[96:99], v[18:19], v[184:185], v[96:99]
	v_exp_f32_e32 v84, v84
	v_exp_f32_e32 v85, v85
	v_exp_f32_e32 v86, v86
	v_exp_f32_e32 v87, v87
	v_pk_fma_f32 v[88:89], v[88:89], s[10:11], v[200:201] op_sel_hi:[1,1,0]
	v_pk_fma_f32 v[90:91], v[90:91], s[10:11], v[200:201] op_sel_hi:[1,1,0]
	v_exp_f32_e32 v88, v88
	v_exp_f32_e32 v89, v89
	v_exp_f32_e32 v90, v90
	v_exp_f32_e32 v91, v91
	v_pk_fma_f32 v[92:93], v[92:93], s[10:11], v[200:201] op_sel_hi:[1,1,0]
	v_pk_fma_f32 v[94:95], v[94:95], s[10:11], v[200:201] op_sel_hi:[1,1,0]
	v_pk_fma_f32 v[96:97], v[96:97], s[10:11], v[200:201] op_sel_hi:[1,1,0]
	v_pk_fma_f32 v[98:99], v[98:99], s[10:11], v[200:201] op_sel_hi:[1,1,0]
	v_exp_f32_e32 v92, v92
	v_exp_f32_e32 v93, v93
	v_exp_f32_e32 v94, v94
	v_exp_f32_e32 v95, v95
	s_nop 0
	v_exp_f32_e32 v96, v96
	v_exp_f32_e32 v97, v97
	v_exp_f32_e32 v98, v98
	v_exp_f32_e32 v99, v99
	v_pk_add_f32 v[248:249], v[84:85], v[86:87]
	v_pk_add_f32 v[82:83], v[88:89], v[90:91]
	v_pk_add_f32 v[172:173], v[92:93], v[94:95]
	v_pk_add_f32 v[202:203], v[96:97], v[98:99]
	v_cvt_pk_fp8_f32 v84, v84, v85
	v_cvt_pk_fp8_f32 v85, v88, v89
	v_pk_add_f32 v[248:249], v[248:249], v[82:83]
	v_pk_add_f32 v[172:173], v[172:173], v[202:203]
	v_cvt_pk_fp8_f32 v84, v86, v87 op_sel:[0,0,1]
	v_cvt_pk_fp8_f32 v85, v90, v91 op_sel:[0,0,1]
	v_pk_add_f32 v[248:249], v[248:249], v[172:173]
	v_cvt_pk_fp8_f32 v86, v92, v93
	v_cvt_pk_fp8_f32 v87, v96, v97
	v_add_f32_e32 v248, v248, v249
	v_cvt_pk_fp8_f32 v86, v94, v95 op_sel:[0,0,1]
	v_cvt_pk_fp8_f32 v87, v98, v99 op_sel:[0,0,1]
	v_cmp_lt_f32_e32 vcc, 0x43800000, v248
	s_cbranch_vccnz .Lbm3_Ag2_redo
	s_lshr_b32 s83, s48, 12
	s_cmp_lg_u32 s83, 0
	s_cbranch_scc1 .Lbm3_Ag2_ks0
	s_lshl_b32 s83, s32, 12
	s_add_u32 s30, s40, s83
	s_addc_u32 s31, s41, 0
	global_load_dwordx4 v[2:5], v79, s[30:31]
	global_load_dwordx4 v[6:9], v79, s[30:31] offset:1024
	global_load_dwordx4 v[12:15], v79, s[30:31] offset:2048
	global_load_dwordx4 v[16:19], v79, s[30:31] offset:3072

.Lbm3_Ag2_exp:
	v_exp_f32_e32 v84, v84
	v_exp_f32_e32 v85, v85
	v_exp_f32_e32 v86, v86
	v_exp_f32_e32 v87, v87
	v_exp_f32_e32 v88, v88
	v_exp_f32_e32 v89, v89
	v_exp_f32_e32 v90, v90
	v_exp_f32_e32 v91, v91
	v_exp_f32_e32 v92, v92
	v_exp_f32_e32 v93, v93
	v_exp_f32_e32 v94, v94
	v_exp_f32_e32 v95, v95
	v_exp_f32_e32 v96, v96
	v_exp_f32_e32 v97, v97
	v_exp_f32_e32 v98, v98
	v_exp_f32_e32 v99, v99
	v_pk_add_f32 v[248:249], v[84:85], v[86:87]
	v_pk_add_f32 v[248:249], v[248:249], v[88:89]
	v_pk_add_f32 v[248:249], v[248:249], v[90:91]
	v_pk_add_f32 v[248:249], v[248:249], v[92:93]
	v_pk_add_f32 v[248:249], v[248:249], v[94:95]
	v_pk_add_f32 v[248:249], v[248:249], v[96:97]
	v_pk_add_f32 v[248:249], v[248:249], v[98:99]
	v_cvt_pk_fp8_f32 v84, v84, v85
	v_cvt_pk_fp8_f32 v85, v88, v89
	v_cvt_pk_fp8_f32 v84, v86, v87 op_sel:[0,0,1]
	v_cvt_pk_fp8_f32 v85, v90, v91 op_sel:[0,0,1]
	v_cvt_pk_fp8_f32 v86, v92, v93
	v_cvt_pk_fp8_f32 v87, v96, v97
	v_cvt_pk_fp8_f32 v86, v94, v95 op_sel:[0,0,1]
	v_cvt_pk_fp8_f32 v87, v98, v99 op_sel:[0,0,1]
	v_add_f32_e32 v248, v248, v249
	v_add_f32_e32 v196, v196, v248
	s_lshr_b32 s83, s48, 12
	s_cmp_lg_u32 s83, 0
	s_cbranch_scc1 .Lbm3_Ag2_ks1
	s_lshl_b32 s83, s32, 12
	s_add_u32 s30, s40, s83
	s_addc_u32 s31, s41, 0
	global_load_dwordx4 v[2:5], v79, s[30:31]
	global_load_dwordx4 v[6:9], v79, s[30:31] offset:1024
	global_load_dwordx4 v[12:15], v79, s[30:31] offset:2048
	global_load_dwordx4 v[16:19], v79, s[30:31] offset:3072

.Lbm3_Ag2_skip:
	s_bfe_u32 s29, s48, 0x4000c
	s_cmp_eq_u32 s29, 0
	s_cbranch_scc1 .Lbm3_Ag3_skip
	s_waitcnt vmcnt(12)
	v_mfma_f32_16x16x32_fp8_fp8 v[84:87], v[2:3], v[186:187], 0
	v_mfma_f32_16x16x32_fp8_fp8 v[84:87], v[4:5], v[188:189], v[84:87]
	v_mfma_f32_16x16x32_fp8_fp8 v[88:91], v[6:7], v[186:187], 0
	v_mfma_f32_16x16x32_fp8_fp8 v[88:91], v[8:9], v[188:189], v[88:91]
	v_and_b32_e32 v199, s29, v244
	s_cmp_eq_u32 s50, 1
	v_cmp_ne_u32_e32 vcc, 0, v199
	s_cbranch_scc1 .Lbm3_Ag3_near0
	v_add_f32_e32 v200, v81, v193
	v_cndmask_b32_e32 v200, v77, v200, vcc
	s_cmp_eq_u32 s35, 0
	s_cbranch_scc1 .Lbm3_Ag3_first0
	v_mfma_f32_16x16x32_fp8_fp8 v[92:95], v[12:13], v[186:187], 0
	v_mfma_f32_16x16x32_fp8_fp8 v[92:95], v[14:15], v[188:189], v[92:95]
	v_pk_fma_f32 v[84:85], v[84:85], s[10:11], v[200:201] op_sel_hi:[1,1,0]
	v_pk_fma_f32 v[86:87], v[86:87], s[10:11], v[200:201] op_sel_hi:[1,1,0]
	v_mfma_f32_16x16x32_fp8_fp8 v[96:99], v[16:17], v[186:187], 0
	v_mfma_f32_16x16x32_fp8_fp8 v[96:99], v[18:19], v[188:189], v[96:99]
	v_exp_f32_e32 v84, v84
	v_exp_f32_e32 v85, v85
	v_exp_f32_e32 v86, v86
	v_exp_f32_e32 v87, v87
	v_pk_fma_f32 v[88:89], v[88:89], s[10:11], v[200:201] op_sel_hi:[1,1,0]
	v_pk_fma_f32 v[90:91], v[90:91], s[10:11], v[200:201] op_sel_hi:[1,1,0]
	v_exp_f32_e32 v88, v88
	v_exp_f32_e32 v89, v89
	v_exp_f32_e32 v90, v90
	v_exp_f32_e32 v91, v91
	v_pk_fma_f32 v[92:93], v[92:93], s[10:11], v[200:201] op_sel_hi:[1,1,0]
	v_pk_fma_f32 v[94:95], v[94:95], s[10:11], v[200:201] op_sel_hi:[1,1,0]
	v_pk_fma_f32 v[96:97], v[96:97], s[10:11], v[200:201] op_sel_hi:[1,1,0]
	v_pk_fma_f32 v[98:99], v[98:99], s[10:11], v[200:201] op_sel_hi:[1,1,0]
	v_exp_f32_e32 v92, v92
	v_exp_f32_e32 v93, v93
	v_exp_f32_e32 v94, v94
	v_exp_f32_e32 v95, v95
	s_nop 0
	v_exp_f32_e32 v96, v96
	v_exp_f32_e32 v97, v97
	v_exp_f32_e32 v98, v98
	v_exp_f32_e32 v99, v99
	v_pk_add_f32 v[248:249], v[84:85], v[86:87]
	v_pk_add_f32 v[82:83], v[88:89], v[90:91]
	v_pk_add_f32 v[172:173], v[92:93], v[94:95]
	v_pk_add_f32 v[202:203], v[96:97], v[98:99]
	v_cvt_pk_fp8_f32 v84, v84, v85
	v_cvt_pk_fp8_f32 v85, v88, v89
	v_pk_add_f32 v[248:249], v[248:249], v[82:83]
	v_pk_add_f32 v[172:173], v[172:173], v[202:203]
	v_cvt_pk_fp8_f32 v84, v86, v87 op_sel:[0,0,1]
	v_cvt_pk_fp8_f32 v85, v90, v91 op_sel:[0,0,1]
	v_pk_add_f32 v[248:249], v[248:249], v[172:173]
	v_cvt_pk_fp8_f32 v86, v92, v93
	v_cvt_pk_fp8_f32 v87, v96, v97
	v_add_f32_e32 v248, v248, v249
	v_cvt_pk_fp8_f32 v86, v94, v95 op_sel:[0,0,1]
	v_cvt_pk_fp8_f32 v87, v98, v99 op_sel:[0,0,1]
	v_cmp_lt_f32_e32 vcc, 0x43800000, v248
	s_cbranch_vccnz .Lbm3_Ag3_redo
	s_lshl_b32 s83, s32, 12
	s_add_u32 s30, s40, s83
	s_addc_u32 s31, s41, 0
	global_load_dwordx4 v[2:5], v79, s[30:31]
	global_load_dwordx4 v[6:9], v79, s[30:31] offset:1024
	global_load_dwordx4 v[12:15], v79, s[30:31] offset:2048
	global_load_dwordx4 v[16:19], v79, s[30:31] offset:3072
	v_add_f32_e32 v197, v197, v248
	s_waitcnt vmcnt(8)
	v_mfma_f32_16x16x32_fp8_fp8 v[148:151], v[36:37], v[84:85], v[148:151]
	v_mfma_f32_16x16x32_fp8_fp8 v[152:155], v[38:39], v[84:85], v[152:155]
	v_mfma_f32_16x16x32_fp8_fp8 v[156:159], v[40:41], v[84:85], v[156:159]
	v_mfma_f32_16x16x32_fp8_fp8 v[160:163], v[42:43], v[84:85], v[160:163]
	v_mfma_f32_16x16x32_fp8_fp8 v[148:151], v[44:45], v[86:87], v[148:151]
	v_mfma_f32_16x16x32_fp8_fp8 v[152:155], v[46:47], v[86:87], v[152:155]
	v_mfma_f32_16x16x32_fp8_fp8 v[156:159], v[48:49], v[86:87], v[156:159]
	v_mfma_f32_16x16x32_fp8_fp8 v[160:163], v[50:51], v[86:87], v[160:163]
	s_branch .Lbm3_Ag3_skip

.Lbm3_Ag3_exp:
	v_exp_f32_e32 v84, v84
	v_exp_f32_e32 v85, v85
	v_exp_f32_e32 v86, v86
	v_exp_f32_e32 v87, v87
	v_exp_f32_e32 v88, v88
	v_exp_f32_e32 v89, v89
	v_exp_f32_e32 v90, v90
	v_exp_f32_e32 v91, v91
	v_exp_f32_e32 v92, v92
	v_exp_f32_e32 v93, v93
	v_exp_f32_e32 v94, v94
	v_exp_f32_e32 v95, v95
	v_exp_f32_e32 v96, v96
	v_exp_f32_e32 v97, v97
	v_exp_f32_e32 v98, v98
	v_exp_f32_e32 v99, v99
	v_pk_add_f32 v[248:249], v[84:85], v[86:87]
	v_pk_add_f32 v[248:249], v[248:249], v[88:89]
	v_pk_add_f32 v[248:249], v[248:249], v[90:91]
	v_pk_add_f32 v[248:249], v[248:249], v[92:93]
	v_pk_add_f32 v[248:249], v[248:249], v[94:95]
	v_pk_add_f32 v[248:249], v[248:249], v[96:97]
	v_pk_add_f32 v[248:249], v[248:249], v[98:99]
	v_cvt_pk_fp8_f32 v84, v84, v85
	v_cvt_pk_fp8_f32 v85, v88, v89
	v_cvt_pk_fp8_f32 v84, v86, v87 op_sel:[0,0,1]
	v_cvt_pk_fp8_f32 v85, v90, v91 op_sel:[0,0,1]
	v_cvt_pk_fp8_f32 v86, v92, v93
	v_cvt_pk_fp8_f32 v87, v96, v97
	v_cvt_pk_fp8_f32 v86, v94, v95 op_sel:[0,0,1]
	v_cvt_pk_fp8_f32 v87, v98, v99 op_sel:[0,0,1]
	v_add_f32_e32 v248, v248, v249
	v_add_f32_e32 v197, v197, v248
	s_lshl_b32 s83, s32, 12
	s_add_u32 s30, s40, s83
	s_addc_u32 s31, s41, 0
	global_load_dwordx4 v[2:5], v79, s[30:31]
	global_load_dwordx4 v[6:9], v79, s[30:31] offset:1024
	global_load_dwordx4 v[12:15], v79, s[30:31] offset:2048
	global_load_dwordx4 v[16:19], v79, s[30:31] offset:3072
	s_waitcnt vmcnt(8)
	v_mfma_f32_16x16x32_fp8_fp8 v[148:151], v[36:37], v[84:85], v[148:151]
	v_mfma_f32_16x16x32_fp8_fp8 v[152:155], v[38:39], v[84:85], v[152:155]
	v_mfma_f32_16x16x32_fp8_fp8 v[156:159], v[40:41], v[84:85], v[156:159]
	v_mfma_f32_16x16x32_fp8_fp8 v[160:163], v[42:43], v[84:85], v[160:163]
	v_mfma_f32_16x16x32_fp8_fp8 v[148:151], v[44:45], v[86:87], v[148:151]
	v_mfma_f32_16x16x32_fp8_fp8 v[152:155], v[46:47], v[86:87], v[152:155]
	v_mfma_f32_16x16x32_fp8_fp8 v[156:159], v[48:49], v[86:87], v[156:159]
	v_mfma_f32_16x16x32_fp8_fp8 v[160:163], v[50:51], v[86:87], v[160:163]
	s_branch .Lbm3_Ag3_skip

.Lbm3_blkB:
	s_lshl_b32 s29, s27, 12
	s_add_u32 s30, s62, s29
	s_addc_u32 s31, s63, 0
	global_load_dwordx4 v[36:39], v79, s[30:31]
	global_load_dwordx4 v[40:43], v79, s[30:31] offset:1024
	global_load_dwordx4 v[44:47], v79, s[30:31] offset:2048
	global_load_dwordx4 v[48:51], v79, s[30:31] offset:3072
	s_add_i32 s50, s35, 3
	s_add_i32 s9, s25, -1
	s_min_i32 s50, s50, s9
	s_lshl_b32 s9, s50, 2
	s_add_i32 s9, s9, s46
	v_mov_b32_e32 v76, s9
	ds_read_b32 v76, v76 offset:16384
	s_cmp_ge_i32 s38, s21
	s_cselect_b32 s50, 1, 0
	s_bfe_u32 s29, s48, 0x40000
	s_cmp_eq_u32 s29, 0
	s_cbranch_scc1 .Lbm3_Bg0_skip
	s_waitcnt vmcnt(12)
	v_mfma_f32_16x16x32_fp8_fp8 v[84:87], v[20:21], v[164:165], 0
	v_mfma_f32_16x16x32_fp8_fp8 v[84:87], v[22:23], v[166:167], v[84:87]
	v_mfma_f32_16x16x32_fp8_fp8 v[88:91], v[24:25], v[164:165], 0
	v_mfma_f32_16x16x32_fp8_fp8 v[88:91], v[26:27], v[166:167], v[88:91]
	v_and_b32_e32 v199, s29, v244
	s_cmp_eq_u32 s50, 1
	v_cmp_ne_u32_e32 vcc, 0, v199
	s_cbranch_scc1 .Lbm3_Bg0_near0
	v_add_f32_e32 v200, v81, v190
	v_cndmask_b32_e32 v200, v77, v200, vcc
	s_cmp_eq_u32 s35, 0
	s_cbranch_scc1 .Lbm3_Bg0_first0
	v_mfma_f32_16x16x32_fp8_fp8 v[92:95], v[28:29], v[164:165], 0
	v_mfma_f32_16x16x32_fp8_fp8 v[92:95], v[30:31], v[166:167], v[92:95]
	v_pk_fma_f32 v[84:85], v[84:85], s[10:11], v[200:201] op_sel_hi:[1,1,0]
	v_pk_fma_f32 v[86:87], v[86:87], s[10:11], v[200:201] op_sel_hi:[1,1,0]
	v_mfma_f32_16x16x32_fp8_fp8 v[96:99], v[32:33], v[164:165], 0
	v_mfma_f32_16x16x32_fp8_fp8 v[96:99], v[34:35], v[166:167], v[96:99]
	v_exp_f32_e32 v84, v84
	v_exp_f32_e32 v85, v85
	v_exp_f32_e32 v86, v86
	v_exp_f32_e32 v87, v87
	v_pk_fma_f32 v[88:89], v[88:89], s[10:11], v[200:201] op_sel_hi:[1,1,0]
	v_pk_fma_f32 v[90:91], v[90:91], s[10:11], v[200:201] op_sel_hi:[1,1,0]
	v_exp_f32_e32 v88, v88
	v_exp_f32_e32 v89, v89
	v_exp_f32_e32 v90, v90
	v_exp_f32_e32 v91, v91
	v_pk_fma_f32 v[92:93], v[92:93], s[10:11], v[200:201] op_sel_hi:[1,1,0]
	v_pk_fma_f32 v[94:95], v[94:95], s[10:11], v[200:201] op_sel_hi:[1,1,0]
	v_pk_fma_f32 v[96:97], v[96:97], s[10:11], v[200:201] op_sel_hi:[1,1,0]
	v_pk_fma_f32 v[98:99], v[98:99], s[10:11], v[200:201] op_sel_hi:[1,1,0]
	v_exp_f32_e32 v92, v92
	v_exp_f32_e32 v93, v93
	v_exp_f32_e32 v94, v94
	v_exp_f32_e32 v95, v95
	s_nop 0
	v_exp_f32_e32 v96, v96
	v_exp_f32_e32 v97, v97
	v_exp_f32_e32 v98, v98
	v_exp_f32_e32 v99, v99
	v_pk_add_f32 v[248:249], v[84:85], v[86:87]
	v_pk_add_f32 v[82:83], v[88:89], v[90:91]
	v_pk_add_f32 v[172:173], v[92:93], v[94:95]
	v_pk_add_f32 v[202:203], v[96:97], v[98:99]
	v_cvt_pk_fp8_f32 v84, v84, v85
	v_cvt_pk_fp8_f32 v85, v88, v89
	v_pk_add_f32 v[248:249], v[248:249], v[82:83]
	v_pk_add_f32 v[172:173], v[172:173], v[202:203]
	v_cvt_pk_fp8_f32 v84, v86, v87 op_sel:[0,0,1]
	v_cvt_pk_fp8_f32 v85, v90, v91 op_sel:[0,0,1]
	v_pk_add_f32 v[248:249], v[248:249], v[172:173]
	v_cvt_pk_fp8_f32 v86, v92, v93
	v_cvt_pk_fp8_f32 v87, v96, v97
	v_add_f32_e32 v248, v248, v249
	v_cvt_pk_fp8_f32 v86, v94, v95 op_sel:[0,0,1]
	v_cvt_pk_fp8_f32 v87, v98, v99 op_sel:[0,0,1]
	v_cmp_lt_f32_e32 vcc, 0x43800000, v248
	s_cbranch_vccnz .Lbm3_Bg0_redo
	s_lshr_b32 s83, s48, 4
	s_cmp_lg_u32 s83, 0
	s_cbranch_scc1 .Lbm3_Bg0_ks0
	s_lshl_b32 s83, s32, 12
	s_add_u32 s30, s40, s83
	s_addc_u32 s31, s41, 0
	global_load_dwordx4 v[20:23], v79, s[30:31]
	global_load_dwordx4 v[24:27], v79, s[30:31] offset:1024
	global_load_dwordx4 v[28:31], v79, s[30:31] offset:2048
	global_load_dwordx4 v[32:35], v79, s[30:31] offset:3072

.Lbm3_Bg0_exp:
	v_exp_f32_e32 v84, v84
	v_exp_f32_e32 v85, v85
	v_exp_f32_e32 v86, v86
	v_exp_f32_e32 v87, v87
	v_exp_f32_e32 v88, v88
	v_exp_f32_e32 v89, v89
	v_exp_f32_e32 v90, v90
	v_exp_f32_e32 v91, v91
	v_exp_f32_e32 v92, v92
	v_exp_f32_e32 v93, v93
	v_exp_f32_e32 v94, v94
	v_exp_f32_e32 v95, v95
	v_exp_f32_e32 v96, v96
	v_exp_f32_e32 v97, v97
	v_exp_f32_e32 v98, v98
	v_exp_f32_e32 v99, v99
	v_pk_add_f32 v[248:249], v[84:85], v[86:87]
	v_pk_add_f32 v[248:249], v[248:249], v[88:89]
	v_pk_add_f32 v[248:249], v[248:249], v[90:91]
	v_pk_add_f32 v[248:249], v[248:249], v[92:93]
	v_pk_add_f32 v[248:249], v[248:249], v[94:95]
	v_pk_add_f32 v[248:249], v[248:249], v[96:97]
	v_pk_add_f32 v[248:249], v[248:249], v[98:99]
	v_cvt_pk_fp8_f32 v84, v84, v85
	v_cvt_pk_fp8_f32 v85, v88, v89
	v_cvt_pk_fp8_f32 v84, v86, v87 op_sel:[0,0,1]
	v_cvt_pk_fp8_f32 v85, v90, v91 op_sel:[0,0,1]
	v_cvt_pk_fp8_f32 v86, v92, v93
	v_cvt_pk_fp8_f32 v87, v96, v97
	v_cvt_pk_fp8_f32 v86, v94, v95 op_sel:[0,0,1]
	v_cvt_pk_fp8_f32 v87, v98, v99 op_sel:[0,0,1]
	v_add_f32_e32 v248, v248, v249
	v_add_f32_e32 v194, v194, v248
	s_lshr_b32 s83, s48, 4
	s_cmp_lg_u32 s83, 0
	s_cbranch_scc1 .Lbm3_Bg0_ks1
	s_lshl_b32 s83, s32, 12
	s_add_u32 s30, s40, s83
	s_addc_u32 s31, s41, 0
	global_load_dwordx4 v[20:23], v79, s[30:31]
	global_load_dwordx4 v[24:27], v79, s[30:31] offset:1024
	global_load_dwordx4 v[28:31], v79, s[30:31] offset:2048
	global_load_dwordx4 v[32:35], v79, s[30:31] offset:3072

.Lbm3_Bg0_skip:
	s_bfe_u32 s29, s48, 0x40004
	s_cmp_eq_u32 s29, 0
	s_cbranch_scc1 .Lbm3_Bg1_skip
	s_waitcnt vmcnt(12)
	v_mfma_f32_16x16x32_fp8_fp8 v[84:87], v[20:21], v[168:169], 0
	v_mfma_f32_16x16x32_fp8_fp8 v[84:87], v[22:23], v[170:171], v[84:87]
	v_mfma_f32_16x16x32_fp8_fp8 v[88:91], v[24:25], v[168:169], 0
	v_mfma_f32_16x16x32_fp8_fp8 v[88:91], v[26:27], v[170:171], v[88:91]
	v_and_b32_e32 v199, s29, v244
	s_cmp_eq_u32 s50, 1
	v_cmp_ne_u32_e32 vcc, 0, v199
	s_cbranch_scc1 .Lbm3_Bg1_near0
	v_add_f32_e32 v200, v81, v191
	v_cndmask_b32_e32 v200, v77, v200, vcc
	s_cmp_eq_u32 s35, 0
	s_cbranch_scc1 .Lbm3_Bg1_first0
	v_mfma_f32_16x16x32_fp8_fp8 v[92:95], v[28:29], v[168:169], 0
	v_mfma_f32_16x16x32_fp8_fp8 v[92:95], v[30:31], v[170:171], v[92:95]
	v_pk_fma_f32 v[84:85], v[84:85], s[10:11], v[200:201] op_sel_hi:[1,1,0]
	v_pk_fma_f32 v[86:87], v[86:87], s[10:11], v[200:201] op_sel_hi:[1,1,0]
	v_mfma_f32_16x16x32_fp8_fp8 v[96:99], v[32:33], v[168:169], 0
	v_mfma_f32_16x16x32_fp8_fp8 v[96:99], v[34:35], v[170:171], v[96:99]
	v_exp_f32_e32 v84, v84
	v_exp_f32_e32 v85, v85
	v_exp_f32_e32 v86, v86
	v_exp_f32_e32 v87, v87
	v_pk_fma_f32 v[88:89], v[88:89], s[10:11], v[200:201] op_sel_hi:[1,1,0]
	v_pk_fma_f32 v[90:91], v[90:91], s[10:11], v[200:201] op_sel_hi:[1,1,0]
	v_exp_f32_e32 v88, v88
	v_exp_f32_e32 v89, v89
	v_exp_f32_e32 v90, v90
	v_exp_f32_e32 v91, v91
	v_pk_fma_f32 v[92:93], v[92:93], s[10:11], v[200:201] op_sel_hi:[1,1,0]
	v_pk_fma_f32 v[94:95], v[94:95], s[10:11], v[200:201] op_sel_hi:[1,1,0]
	v_pk_fma_f32 v[96:97], v[96:97], s[10:11], v[200:201] op_sel_hi:[1,1,0]
	v_pk_fma_f32 v[98:99], v[98:99], s[10:11], v[200:201] op_sel_hi:[1,1,0]
	v_exp_f32_e32 v92, v92
	v_exp_f32_e32 v93, v93
	v_exp_f32_e32 v94, v94
	v_exp_f32_e32 v95, v95
	s_nop 0
	v_exp_f32_e32 v96, v96
	v_exp_f32_e32 v97, v97
	v_exp_f32_e32 v98, v98
	v_exp_f32_e32 v99, v99
	v_pk_add_f32 v[248:249], v[84:85], v[86:87]
	v_pk_add_f32 v[82:83], v[88:89], v[90:91]
	v_pk_add_f32 v[172:173], v[92:93], v[94:95]
	v_pk_add_f32 v[202:203], v[96:97], v[98:99]
	v_cvt_pk_fp8_f32 v84, v84, v85
	v_cvt_pk_fp8_f32 v85, v88, v89
	v_pk_add_f32 v[248:249], v[248:249], v[82:83]
	v_pk_add_f32 v[172:173], v[172:173], v[202:203]
	v_cvt_pk_fp8_f32 v84, v86, v87 op_sel:[0,0,1]
	v_cvt_pk_fp8_f32 v85, v90, v91 op_sel:[0,0,1]
	v_pk_add_f32 v[248:249], v[248:249], v[172:173]
	v_cvt_pk_fp8_f32 v86, v92, v93
	v_cvt_pk_fp8_f32 v87, v96, v97
	v_add_f32_e32 v248, v248, v249
	v_cvt_pk_fp8_f32 v86, v94, v95 op_sel:[0,0,1]
	v_cvt_pk_fp8_f32 v87, v98, v99 op_sel:[0,0,1]
	v_cmp_lt_f32_e32 vcc, 0x43800000, v248
	s_cbranch_vccnz .Lbm3_Bg1_redo
	s_lshr_b32 s83, s48, 8
	s_cmp_lg_u32 s83, 0
	s_cbranch_scc1 .Lbm3_Bg1_ks0
	s_lshl_b32 s83, s32, 12
	s_add_u32 s30, s40, s83
	s_addc_u32 s31, s41, 0
	global_load_dwordx4 v[20:23], v79, s[30:31]
	global_load_dwordx4 v[24:27], v79, s[30:31] offset:1024
	global_load_dwordx4 v[28:31], v79, s[30:31] offset:2048
	global_load_dwordx4 v[32:35], v79, s[30:31] offset:3072

.Lbm3_Bg1_exp:
	v_exp_f32_e32 v84, v84
	v_exp_f32_e32 v85, v85
	v_exp_f32_e32 v86, v86
	v_exp_f32_e32 v87, v87
	v_exp_f32_e32 v88, v88
	v_exp_f32_e32 v89, v89
	v_exp_f32_e32 v90, v90
	v_exp_f32_e32 v91, v91
	v_exp_f32_e32 v92, v92
	v_exp_f32_e32 v93, v93
	v_exp_f32_e32 v94, v94
	v_exp_f32_e32 v95, v95
	v_exp_f32_e32 v96, v96
	v_exp_f32_e32 v97, v97
	v_exp_f32_e32 v98, v98
	v_exp_f32_e32 v99, v99
	v_pk_add_f32 v[248:249], v[84:85], v[86:87]
	v_pk_add_f32 v[248:249], v[248:249], v[88:89]
	v_pk_add_f32 v[248:249], v[248:249], v[90:91]
	v_pk_add_f32 v[248:249], v[248:249], v[92:93]
	v_pk_add_f32 v[248:249], v[248:249], v[94:95]
	v_pk_add_f32 v[248:249], v[248:249], v[96:97]
	v_pk_add_f32 v[248:249], v[248:249], v[98:99]
	v_cvt_pk_fp8_f32 v84, v84, v85
	v_cvt_pk_fp8_f32 v85, v88, v89
	v_cvt_pk_fp8_f32 v84, v86, v87 op_sel:[0,0,1]
	v_cvt_pk_fp8_f32 v85, v90, v91 op_sel:[0,0,1]
	v_cvt_pk_fp8_f32 v86, v92, v93
	v_cvt_pk_fp8_f32 v87, v96, v97
	v_cvt_pk_fp8_f32 v86, v94, v95 op_sel:[0,0,1]
	v_cvt_pk_fp8_f32 v87, v98, v99 op_sel:[0,0,1]
	v_add_f32_e32 v248, v248, v249
	v_add_f32_e32 v195, v195, v248
	s_lshr_b32 s83, s48, 8
	s_cmp_lg_u32 s83, 0
	s_cbranch_scc1 .Lbm3_Bg1_ks1
	s_lshl_b32 s83, s32, 12
	s_add_u32 s30, s40, s83
	s_addc_u32 s31, s41, 0
	global_load_dwordx4 v[20:23], v79, s[30:31]
	global_load_dwordx4 v[24:27], v79, s[30:31] offset:1024
	global_load_dwordx4 v[28:31], v79, s[30:31] offset:2048
	global_load_dwordx4 v[32:35], v79, s[30:31] offset:3072

.Lbm3_Bg1_skip:
	s_bfe_u32 s29, s48, 0x40008
	s_cmp_eq_u32 s29, 0
	s_cbranch_scc1 .Lbm3_Bg2_skip
	s_waitcnt vmcnt(12)
	v_mfma_f32_16x16x32_fp8_fp8 v[84:87], v[20:21], v[182:183], 0
	v_mfma_f32_16x16x32_fp8_fp8 v[84:87], v[22:23], v[184:185], v[84:87]
	v_mfma_f32_16x16x32_fp8_fp8 v[88:91], v[24:25], v[182:183], 0
	v_mfma_f32_16x16x32_fp8_fp8 v[88:91], v[26:27], v[184:185], v[88:91]
	v_and_b32_e32 v199, s29, v244
	s_cmp_eq_u32 s50, 1
	v_cmp_ne_u32_e32 vcc, 0, v199
	s_cbranch_scc1 .Lbm3_Bg2_near0
	v_add_f32_e32 v200, v81, v192
	v_cndmask_b32_e32 v200, v77, v200, vcc
	s_cmp_eq_u32 s35, 0
	s_cbranch_scc1 .Lbm3_Bg2_first0
	v_mfma_f32_16x16x32_fp8_fp8 v[92:95], v[28:29], v[182:183], 0
	v_mfma_f32_16x16x32_fp8_fp8 v[92:95], v[30:31], v[184:185], v[92:95]
	v_pk_fma_f32 v[84:85], v[84:85], s[10:11], v[200:201] op_sel_hi:[1,1,0]
	v_pk_fma_f32 v[86:87], v[86:87], s[10:11], v[200:201] op_sel_hi:[1,1,0]
	v_mfma_f32_16x16x32_fp8_fp8 v[96:99], v[32:33], v[182:183], 0
	v_mfma_f32_16x16x32_fp8_fp8 v[96:99], v[34:35], v[184:185], v[96:99]
	v_exp_f32_e32 v84, v84
	v_exp_f32_e32 v85, v85
	v_exp_f32_e32 v86, v86
	v_exp_f32_e32 v87, v87
	v_pk_fma_f32 v[88:89], v[88:89], s[10:11], v[200:201] op_sel_hi:[1,1,0]
	v_pk_fma_f32 v[90:91], v[90:91], s[10:11], v[200:201] op_sel_hi:[1,1,0]
	v_exp_f32_e32 v88, v88
	v_exp_f32_e32 v89, v89
	v_exp_f32_e32 v90, v90
	v_exp_f32_e32 v91, v91
	v_pk_fma_f32 v[92:93], v[92:93], s[10:11], v[200:201] op_sel_hi:[1,1,0]
	v_pk_fma_f32 v[94:95], v[94:95], s[10:11], v[200:201] op_sel_hi:[1,1,0]
	v_pk_fma_f32 v[96:97], v[96:97], s[10:11], v[200:201] op_sel_hi:[1,1,0]
	v_pk_fma_f32 v[98:99], v[98:99], s[10:11], v[200:201] op_sel_hi:[1,1,0]
	v_exp_f32_e32 v92, v92
	v_exp_f32_e32 v93, v93
	v_exp_f32_e32 v94, v94
	v_exp_f32_e32 v95, v95
	s_nop 0
	v_exp_f32_e32 v96, v96
	v_exp_f32_e32 v97, v97
	v_exp_f32_e32 v98, v98
	v_exp_f32_e32 v99, v99
	v_pk_add_f32 v[248:249], v[84:85], v[86:87]
	v_pk_add_f32 v[82:83], v[88:89], v[90:91]
	v_pk_add_f32 v[172:173], v[92:93], v[94:95]
	v_pk_add_f32 v[202:203], v[96:97], v[98:99]
	v_cvt_pk_fp8_f32 v84, v84, v85
	v_cvt_pk_fp8_f32 v85, v88, v89
	v_pk_add_f32 v[248:249], v[248:249], v[82:83]
	v_pk_add_f32 v[172:173], v[172:173], v[202:203]
	v_cvt_pk_fp8_f32 v84, v86, v87 op_sel:[0,0,1]
	v_cvt_pk_fp8_f32 v85, v90, v91 op_sel:[0,0,1]
	v_pk_add_f32 v[248:249], v[248:249], v[172:173]
	v_cvt_pk_fp8_f32 v86, v92, v93
	v_cvt_pk_fp8_f32 v87, v96, v97
	v_add_f32_e32 v248, v248, v249
	v_cvt_pk_fp8_f32 v86, v94, v95 op_sel:[0,0,1]
	v_cvt_pk_fp8_f32 v87, v98, v99 op_sel:[0,0,1]
	v_cmp_lt_f32_e32 vcc, 0x43800000, v248
	s_cbranch_vccnz .Lbm3_Bg2_redo
	s_lshr_b32 s83, s48, 12
	s_cmp_lg_u32 s83, 0
	s_cbranch_scc1 .Lbm3_Bg2_ks0
	s_lshl_b32 s83, s32, 12
	s_add_u32 s30, s40, s83
	s_addc_u32 s31, s41, 0
	global_load_dwordx4 v[20:23], v79, s[30:31]
	global_load_dwordx4 v[24:27], v79, s[30:31] offset:1024
	global_load_dwordx4 v[28:31], v79, s[30:31] offset:2048
	global_load_dwordx4 v[32:35], v79, s[30:31] offset:3072

.Lbm3_Bg2_exp:
	v_exp_f32_e32 v84, v84
	v_exp_f32_e32 v85, v85
	v_exp_f32_e32 v86, v86
	v_exp_f32_e32 v87, v87
	v_exp_f32_e32 v88, v88
	v_exp_f32_e32 v89, v89
	v_exp_f32_e32 v90, v90
	v_exp_f32_e32 v91, v91
	v_exp_f32_e32 v92, v92
	v_exp_f32_e32 v93, v93
	v_exp_f32_e32 v94, v94
	v_exp_f32_e32 v95, v95
	v_exp_f32_e32 v96, v96
	v_exp_f32_e32 v97, v97
	v_exp_f32_e32 v98, v98
	v_exp_f32_e32 v99, v99
	v_pk_add_f32 v[248:249], v[84:85], v[86:87]
	v_pk_add_f32 v[248:249], v[248:249], v[88:89]
	v_pk_add_f32 v[248:249], v[248:249], v[90:91]
	v_pk_add_f32 v[248:249], v[248:249], v[92:93]
	v_pk_add_f32 v[248:249], v[248:249], v[94:95]
	v_pk_add_f32 v[248:249], v[248:249], v[96:97]
	v_pk_add_f32 v[248:249], v[248:249], v[98:99]
	v_cvt_pk_fp8_f32 v84, v84, v85
	v_cvt_pk_fp8_f32 v85, v88, v89
	v_cvt_pk_fp8_f32 v84, v86, v87 op_sel:[0,0,1]
	v_cvt_pk_fp8_f32 v85, v90, v91 op_sel:[0,0,1]
	v_cvt_pk_fp8_f32 v86, v92, v93
	v_cvt_pk_fp8_f32 v87, v96, v97
	v_cvt_pk_fp8_f32 v86, v94, v95 op_sel:[0,0,1]
	v_cvt_pk_fp8_f32 v87, v98, v99 op_sel:[0,0,1]
	v_add_f32_e32 v248, v248, v249
	v_add_f32_e32 v196, v196, v248
	s_lshr_b32 s83, s48, 12
	s_cmp_lg_u32 s83, 0
	s_cbranch_scc1 .Lbm3_Bg2_ks1
	s_lshl_b32 s83, s32, 12
	s_add_u32 s30, s40, s83
	s_addc_u32 s31, s41, 0
	global_load_dwordx4 v[20:23], v79, s[30:31]
	global_load_dwordx4 v[24:27], v79, s[30:31] offset:1024
	global_load_dwordx4 v[28:31], v79, s[30:31] offset:2048
	global_load_dwordx4 v[32:35], v79, s[30:31] offset:3072

.Lbm3_Bg2_skip:
	s_bfe_u32 s29, s48, 0x4000c
	s_cmp_eq_u32 s29, 0
	s_cbranch_scc1 .Lbm3_Bg3_skip
	s_waitcnt vmcnt(12)
	v_mfma_f32_16x16x32_fp8_fp8 v[84:87], v[20:21], v[186:187], 0
	v_mfma_f32_16x16x32_fp8_fp8 v[84:87], v[22:23], v[188:189], v[84:87]
	v_mfma_f32_16x16x32_fp8_fp8 v[88:91], v[24:25], v[186:187], 0
	v_mfma_f32_16x16x32_fp8_fp8 v[88:91], v[26:27], v[188:189], v[88:91]
	v_and_b32_e32 v199, s29, v244
	s_cmp_eq_u32 s50, 1
	v_cmp_ne_u32_e32 vcc, 0, v199
	s_cbranch_scc1 .Lbm3_Bg3_near0
	v_add_f32_e32 v200, v81, v193
	v_cndmask_b32_e32 v200, v77, v200, vcc
	s_cmp_eq_u32 s35, 0
	s_cbranch_scc1 .Lbm3_Bg3_first0
	v_mfma_f32_16x16x32_fp8_fp8 v[92:95], v[28:29], v[186:187], 0
	v_mfma_f32_16x16x32_fp8_fp8 v[92:95], v[30:31], v[188:189], v[92:95]
	v_pk_fma_f32 v[84:85], v[84:85], s[10:11], v[200:201] op_sel_hi:[1,1,0]
	v_pk_fma_f32 v[86:87], v[86:87], s[10:11], v[200:201] op_sel_hi:[1,1,0]
	v_mfma_f32_16x16x32_fp8_fp8 v[96:99], v[32:33], v[186:187], 0
	v_mfma_f32_16x16x32_fp8_fp8 v[96:99], v[34:35], v[188:189], v[96:99]
	v_exp_f32_e32 v84, v84
	v_exp_f32_e32 v85, v85
	v_exp_f32_e32 v86, v86
	v_exp_f32_e32 v87, v87
	v_pk_fma_f32 v[88:89], v[88:89], s[10:11], v[200:201] op_sel_hi:[1,1,0]
	v_pk_fma_f32 v[90:91], v[90:91], s[10:11], v[200:201] op_sel_hi:[1,1,0]
	v_exp_f32_e32 v88, v88
	v_exp_f32_e32 v89, v89
	v_exp_f32_e32 v90, v90
	v_exp_f32_e32 v91, v91
	v_pk_fma_f32 v[92:93], v[92:93], s[10:11], v[200:201] op_sel_hi:[1,1,0]
	v_pk_fma_f32 v[94:95], v[94:95], s[10:11], v[200:201] op_sel_hi:[1,1,0]
	v_pk_fma_f32 v[96:97], v[96:97], s[10:11], v[200:201] op_sel_hi:[1,1,0]
	v_pk_fma_f32 v[98:99], v[98:99], s[10:11], v[200:201] op_sel_hi:[1,1,0]
	v_exp_f32_e32 v92, v92
	v_exp_f32_e32 v93, v93
	v_exp_f32_e32 v94, v94
	v_exp_f32_e32 v95, v95
	s_nop 0
	v_exp_f32_e32 v96, v96
	v_exp_f32_e32 v97, v97
	v_exp_f32_e32 v98, v98
	v_exp_f32_e32 v99, v99
	v_pk_add_f32 v[248:249], v[84:85], v[86:87]
	v_pk_add_f32 v[82:83], v[88:89], v[90:91]
	v_pk_add_f32 v[172:173], v[92:93], v[94:95]
	v_pk_add_f32 v[202:203], v[96:97], v[98:99]
	v_cvt_pk_fp8_f32 v84, v84, v85
	v_cvt_pk_fp8_f32 v85, v88, v89
	v_pk_add_f32 v[248:249], v[248:249], v[82:83]
	v_pk_add_f32 v[172:173], v[172:173], v[202:203]
	v_cvt_pk_fp8_f32 v84, v86, v87 op_sel:[0,0,1]
	v_cvt_pk_fp8_f32 v85, v90, v91 op_sel:[0,0,1]
	v_pk_add_f32 v[248:249], v[248:249], v[172:173]
	v_cvt_pk_fp8_f32 v86, v92, v93
	v_cvt_pk_fp8_f32 v87, v96, v97
	v_add_f32_e32 v248, v248, v249
	v_cvt_pk_fp8_f32 v86, v94, v95 op_sel:[0,0,1]
	v_cvt_pk_fp8_f32 v87, v98, v99 op_sel:[0,0,1]
	v_cmp_lt_f32_e32 vcc, 0x43800000, v248
	s_cbranch_vccnz .Lbm3_Bg3_redo
	s_lshl_b32 s83, s32, 12
	s_add_u32 s30, s40, s83
	s_addc_u32 s31, s41, 0
	global_load_dwordx4 v[20:23], v79, s[30:31]
	global_load_dwordx4 v[24:27], v79, s[30:31] offset:1024
	global_load_dwordx4 v[28:31], v79, s[30:31] offset:2048
	global_load_dwordx4 v[32:35], v79, s[30:31] offset:3072
	v_add_f32_e32 v197, v197, v248
	s_waitcnt vmcnt(8)
	v_mfma_f32_16x16x32_fp8_fp8 v[148:151], v[52:53], v[84:85], v[148:151]
	v_mfma_f32_16x16x32_fp8_fp8 v[152:155], v[54:55], v[84:85], v[152:155]
	v_mfma_f32_16x16x32_fp8_fp8 v[156:159], v[56:57], v[84:85], v[156:159]
	v_mfma_f32_16x16x32_fp8_fp8 v[160:163], v[58:59], v[84:85], v[160:163]
	v_mfma_f32_16x16x32_fp8_fp8 v[148:151], v[60:61], v[86:87], v[148:151]
	v_mfma_f32_16x16x32_fp8_fp8 v[152:155], v[62:63], v[86:87], v[152:155]
	v_mfma_f32_16x16x32_fp8_fp8 v[156:159], v[64:65], v[86:87], v[156:159]
	v_mfma_f32_16x16x32_fp8_fp8 v[160:163], v[66:67], v[86:87], v[160:163]
	s_branch .Lbm3_Bg3_skip

.Lbm3_Bg3_exp:
	v_exp_f32_e32 v84, v84
	v_exp_f32_e32 v85, v85
	v_exp_f32_e32 v86, v86
	v_exp_f32_e32 v87, v87
	v_exp_f32_e32 v88, v88
	v_exp_f32_e32 v89, v89
	v_exp_f32_e32 v90, v90
	v_exp_f32_e32 v91, v91
	v_exp_f32_e32 v92, v92
	v_exp_f32_e32 v93, v93
	v_exp_f32_e32 v94, v94
	v_exp_f32_e32 v95, v95
	v_exp_f32_e32 v96, v96
	v_exp_f32_e32 v97, v97
	v_exp_f32_e32 v98, v98
	v_exp_f32_e32 v99, v99
	v_pk_add_f32 v[248:249], v[84:85], v[86:87]
	v_pk_add_f32 v[248:249], v[248:249], v[88:89]
	v_pk_add_f32 v[248:249], v[248:249], v[90:91]
	v_pk_add_f32 v[248:249], v[248:249], v[92:93]
	v_pk_add_f32 v[248:249], v[248:249], v[94:95]
	v_pk_add_f32 v[248:249], v[248:249], v[96:97]
	v_pk_add_f32 v[248:249], v[248:249], v[98:99]
	v_cvt_pk_fp8_f32 v84, v84, v85
	v_cvt_pk_fp8_f32 v85, v88, v89
	v_cvt_pk_fp8_f32 v84, v86, v87 op_sel:[0,0,1]
	v_cvt_pk_fp8_f32 v85, v90, v91 op_sel:[0,0,1]
	v_cvt_pk_fp8_f32 v86, v92, v93
	v_cvt_pk_fp8_f32 v87, v96, v97
	v_cvt_pk_fp8_f32 v86, v94, v95 op_sel:[0,0,1]
	v_cvt_pk_fp8_f32 v87, v98, v99 op_sel:[0,0,1]
	v_add_f32_e32 v248, v248, v249
	v_add_f32_e32 v197, v197, v248
	s_lshl_b32 s83, s32, 12
	s_add_u32 s30, s40, s83
	s_addc_u32 s31, s41, 0
	global_load_dwordx4 v[20:23], v79, s[30:31]
	global_load_dwordx4 v[24:27], v79, s[30:31] offset:1024
	global_load_dwordx4 v[28:31], v79, s[30:31] offset:2048
	global_load_dwordx4 v[32:35], v79, s[30:31] offset:3072
	s_waitcnt vmcnt(8)
	v_mfma_f32_16x16x32_fp8_fp8 v[148:151], v[52:53], v[84:85], v[148:151]
	v_mfma_f32_16x16x32_fp8_fp8 v[152:155], v[54:55], v[84:85], v[152:155]
	v_mfma_f32_16x16x32_fp8_fp8 v[156:159], v[56:57], v[84:85], v[156:159]
	v_mfma_f32_16x16x32_fp8_fp8 v[160:163], v[58:59], v[84:85], v[160:163]
	v_mfma_f32_16x16x32_fp8_fp8 v[148:151], v[60:61], v[86:87], v[148:151]
	v_mfma_f32_16x16x32_fp8_fp8 v[152:155], v[62:63], v[86:87], v[152:155]
	v_mfma_f32_16x16x32_fp8_fp8 v[156:159], v[64:65], v[86:87], v[156:159]
	v_mfma_f32_16x16x32_fp8_fp8 v[160:163], v[66:67], v[86:87], v[160:163]
	s_branch .Lbm3_Bg3_skip
